# GEMM K-loops (all four): phases merged pairwise, 8 barriers per 2 K-tiles instead of 16; stage order unchanged, vmcnt(8) per segment
# speedup vs baseline: 1.0313x; 1.0110x over previous
; __device__ __forceinline__ int tid_opaque(int wv) { return wv * 64 + lane_fresh(); }
; #define PG8_STAGE(bufoff, gbase, voff) do { _Pragma("unroll") for (int _i = 0; _i < 2; ++_i) \
;         __builtin_amdgcn_global_load_lds((const unsigned*)((const char*)(gbase) + (voff)[_i]), (LAS unsigned*)(lds + (bufoff) + ldsw + _i * 8192), 16, 0, 0); } while (0)
; #define PG8_WAIT_V(n) asm volatile("s_waitcnt vmcnt(" #n ")" ::: "memory")
; #define PG8_BAR __builtin_amdgcn_s_barrier()
; template <class Epi>
; __device__ __forceinline__ void gemm_phase(LAS unsigned char* lds, const Gemm g, const StaticOrder& S, const Epi& E, int wv) {
;     const int tid = tid_opaque(wv);
;     const int wid = __builtin_amdgcn_readfirstlane(tid >> 6), lane = tid & 63, wr = wid >> 2, wc = wid & 3, fr = lane & 15, fq = lane >> 4;
;     const int K = g.K, nt = K / BK;
;     unsigned voffA[2], voffB[2];
; #pragma unroll
;     for (int i = 0; i < 2; ++i) { int R, C; stage_rc(tid * 16 + i * 8192, R, C);
;         const int Ra = (R & ~63) + 4 * (R & 15) + ((R >> 4) & 3);
;         voffA[i] = (unsigned)(Ra * K + C) * 2u; voffB[i] = (unsigned)(R * K + C) * 2u; }
;     const size_t kstep = (size_t)(BK * 2);
;     const size_t hstep = (size_t)HALF * K * 2;
;     const size_t tstepA = (size_t)g.a_tile_rows * K * 2;
;     const size_t tstepB = 2 * hstep;
;     const unsigned ldsw = (unsigned)wid * 1024u;
;     const int aoff = lds_byte(wr * 64 + fr, fq * 8), boff = lds_byte(wc * 32 + fr, fq * 8);
;     ...
;     const char* cA = (const char*)g.A + (size_t)cur.pm * tstepA; const char* cB = (const char*)g.Bt + (size_t)cur.pn * tstepB;
;     PG8_STAGE(PG8_SB(0, 0), cB, voffB); PG8_STAGE(PG8_SA(0, 0), cA, voffA); PG8_STAGE(PG8_SB(0, 1), cB + hstep, voffB); PG8_STAGE(PG8_SA(0, 1), cA + hstep, voffA);
;     if (wr == 1) PG8_BAR;
;     PG8_WAIT_V(4); PG8_BAR;
;     PG8_STAGE(PG8_SB(1, 0), cB + kstep, voffB); PG8_STAGE(PG8_SA(1, 0), cA + kstep, voffA); PG8_STAGE(PG8_SB(1, 1), cB + hstep + kstep, voffB);
;     PG8_WAIT_V(6); PG8_BAR;
.LBB0_206:
	s_add_u32 s18, s14, 0x9c77000
	s_addc_u32 s19, s15, 0
	s_add_u32 s20, s14, 0x1652000
	s_addc_u32 s21, s15, 0
	s_add_u32 s22, s14, 0x1656000
	s_mov_b64 s[28:29], 0x80
	s_addc_u32 s23, s15, 0
	s_and_b32 s4, s4, 3
	s_add_i32 m0, s50, 0x18000
	v_lshl_add_u64 v[6:7], v[6:7], 0, s[28:29]
	s_lshl_b32 s55, s5, 6
	s_lshl_b32 s7, s5, 13
	s_lshl_b32 s57, s4, 5
	s_lshl_b32 s9, s4, 12
	s_waitcnt vmcnt(2)
	s_barrier
	global_load_lds_dwordx4 v[6:7], off
	v_lshl_add_u64 v[4:5], v[4:5], 0, s[28:29]
	s_add_i32 m0, s50, 0x1a000
	s_add_i32 s58, s50, 0x8000
	s_add_i32 s59, s50, 0xa000
	global_load_lds_dwordx4 v[4:5], off
	v_lshl_add_u64 v[2:3], v[2:3], 0, s[28:29]
	s_mov_b32 m0, s58
	s_add_u32 s4, s42, 0x40080
	global_load_lds_dwordx4 v[2:3], off
	v_lshl_add_u64 v[0:1], v[0:1], 0, s[28:29]
	s_mov_b32 m0, s59
	s_addc_u32 s5, s43, 0
	global_load_lds_dwordx4 v[0:1], off
	s_add_i32 m0, s50, 0x1c000
	v_lshl_add_u64 v[0:1], s[4:5], 0, v[130:131]
	global_load_lds_dwordx4 v[0:1], off
	v_lshl_add_u64 v[0:1], s[4:5], 0, v[134:135]
	s_add_i32 m0, s50, 0x1e000
	s_mov_b64 s[4:5], 0x40080
	global_load_lds_dwordx4 v[0:1], off
	v_and_b32_e32 v0, 15, v8
	v_and_b32_e32 v1, 48, v8
	v_lshl_or_b32 v0, v0, 6, v1
	v_lshlrev_b32_e32 v1, 2, v8
	v_and_b32_e32 v1, 32, v1
	v_bitop3_b32 v2, v0, s7, v1 bitop3:0xde
	v_bitop3_b32 v152, v0, s9, v1 bitop3:0xde
	v_and_b32_e32 v1, 1, v9
	v_add3_u32 v0, v11, v12, v13
	v_lshlrev_b32_e32 v1, 6, v1
	v_lshl_or_b32 v0, v0, 11, v1
	v_and_b32_e32 v1, 1, v14
	v_lshl_add_u32 v136, v10, 1, v0
	v_add3_u32 v0, v16, v17, v18
	v_lshlrev_b32_e32 v1, 6, v1
	s_waitcnt vmcnt(6)
	s_bitcmp0_b32 s17, 6
	v_lshl_or_b32 v0, v0, 11, v1
	s_cselect_b64 s[10:11], -1, 0
	v_lshl_add_u64 v[138:139], v[136:137], 0, s[4:5]
	v_lshl_add_u32 v136, v15, 1, v0
	s_add_i32 s65, 0, 0x10000
	s_add_i32 s66, 0, 0x14000
	s_ashr_i32 s60, s24, 31
	s_mov_b32 s61, s24
	s_ashr_i32 s64, s2, 31
	v_lshl_add_u64 v[140:141], v[136:137], 0, s[4:5]
	v_mov_b64_e32 v[142:143], 0x38e
	v_mov_b64_e32 v[144:145], 0x38d
	v_add_u32_e32 v153, s65, v152
	v_add_u32_e32 v154, 0, v2
	v_add_u32_e32 v155, s66, v152
	s_movk_i32 s67, 0xe00
	s_barrier
	s_branch .LBB0_208

; #define PG8_STAGE(bufoff, gbase, voff) do { _Pragma("unroll") for (int _i = 0; _i < 2; ++_i) \
;         __builtin_amdgcn_global_load_lds((const unsigned*)((const char*)(gbase) + (voff)[_i]), (LAS unsigned*)(lds + (bufoff) + ldsw + _i * 8192), 16, 0, 0); } while (0)
; #define PG8_LDA(dst, b, h) do { _Pragma("unroll") for (int m = 0; m < 4; ++m) _Pragma("unroll") for (int k = 0; k < 2; ++k) dst[m][k] = *(const LAS bf16x8*)(lds + PG8_SA(b, h) + aoff + m * 2048 + k * 1024); } while (0)
; #define PG8_LDB(dst, b, h) do { _Pragma("unroll") for (int n = 0; n < 2; ++n) _Pragma("unroll") for (int k = 0; k < 2; ++k) dst[n][k] = *(const LAS bf16x8*)(lds + PG8_SB(b, h) + boff + n * 2048 + k * 1024); } while (0)
; #define PG8_MMA(ai, bj, At, Bt) do { __builtin_amdgcn_s_setprio(1); _Pragma("unroll") for (int m = 0; m < 4; ++m) _Pragma("unroll") for (int n = 0; n < 2; ++n) _Pragma("unroll") for (int k = 0; k < 2; ++k) \
;         acc[ai][bj][m][n] = __builtin_amdgcn_mfma_f32_16x16x32_bf16(Bt[n][k], At[m][k], acc[ai][bj][m][n], 0, 0, 0); __builtin_amdgcn_s_setprio(0); } while (0)
; #define PG8_WAIT_V(n) asm volatile("s_waitcnt vmcnt(" #n ")" ::: "memory")
; #define PG8_WAIT_L(n) asm volatile("s_waitcnt lgkmcnt(" #n ")" ::: "memory")
; #define PG8_BAR __builtin_amdgcn_s_barrier()
; #define PG8_SCHED __builtin_amdgcn_sched_barrier(0)
; template <class Epi>
; __device__ __forceinline__ void gemm_phase(LAS unsigned char* lds, const Gemm g, const StaticOrder& S, const Epi& E, int wv) {
;     ...
;             PG8_LDB(B0, 0, 0); PG8_SCHED; PG8_LDA(At, 0, 0); PG8_STAGE(PG8_SA(1, 1), a1 + hstep, voffA);
;             PG8_WAIT_L(8); PG8_BAR; PG8_WAIT_L(0); PG8_MMA(0, 0, At, B0); PG8_BAR; PG8_SCHED;
;             PG8_LDB(B1, 0, 1); PG8_STAGE(PG8_SB(0, 0), b2, voffB);
;             PG8_BAR; PG8_WAIT_L(0); PG8_MMA(0, 1, At, B1); PG8_BAR;
;             PG8_LDA(At, 0, 1); PG8_STAGE(PG8_SA(0, 0), a2, voffA);
;             PG8_BAR; PG8_WAIT_L(0); PG8_MMA(1, 0, At, B0); PG8_BAR; PG8_SCHED;
;             PG8_STAGE(PG8_SB(0, 1), b2 + hstep, voffB);
;             PG8_WAIT_V(6); PG8_BAR; PG8_MMA(1, 1, At, B1); PG8_BAR;
.LBB0_215:
	ds_read_b128 v[146:149], v153
	ds_read_b128 v[156:159], v153 offset:1024
	ds_read_b128 v[160:163], v153 offset:2048
	ds_read_b128 v[164:167], v153 offset:3072
	s_add_u32 s42, s40, 0x100
	s_addc_u32 s43, s41, 0
	s_cmp_eq_u32 s70, 12
	s_cselect_b32 s47, s7, s43
	s_cselect_b32 s46, s9, s42
	s_cselect_b32 s45, s31, s69
	s_cselect_b32 s44, s35, s68
	ds_read_b128 v[168:171], v154
	ds_read_b128 v[172:175], v154 offset:1024
	ds_read_b128 v[176:179], v154 offset:2048
	ds_read_b128 v[180:183], v154 offset:3072
	ds_read_b128 v[184:187], v154 offset:4096
	ds_read_b128 v[188:191], v154 offset:5120
	ds_read_b128 v[192:195], v154 offset:6144
	ds_read_b128 v[196:199], v154 offset:7168
	ds_read_b128 v[200:203], v155
	ds_read_b128 v[204:207], v155 offset:1024
	ds_read_b128 v[208:211], v155 offset:2048
	ds_read_b128 v[212:215], v155 offset:3072
	v_lshl_add_u64 v[252:253], s[40:41], 0, v[138:139]
	s_add_i32 m0, s50, 0xc000
	s_nop 0
	global_load_lds_dwordx4 v[252:253], off
	v_lshl_add_u64 v[252:253], s[40:41], 0, v[140:141]
	s_add_i32 m0, s50, 0xe000
	s_nop 0
	global_load_lds_dwordx4 v[252:253], off
	s_waitcnt vmcnt(8)
	s_waitcnt lgkmcnt(0)
	s_barrier
	s_setprio 1
	v_mfma_f32_16x16x32_bf16 v[124:127], v[146:149], v[168:171], v[124:127]
	v_mfma_f32_16x16x32_bf16 v[120:123], v[160:163], v[168:171], v[120:123]
	v_mfma_f32_16x16x32_bf16 v[108:111], v[146:149], v[176:179], v[108:111]
	v_mfma_f32_16x16x32_bf16 v[104:107], v[160:163], v[176:179], v[104:107]
	v_mfma_f32_16x16x32_bf16 v[92:95], v[146:149], v[184:187], v[92:95]
	v_mfma_f32_16x16x32_bf16 v[88:91], v[160:163], v[184:187], v[88:91]
	v_mfma_f32_16x16x32_bf16 v[76:79], v[146:149], v[192:195], v[76:79]
	v_mfma_f32_16x16x32_bf16 v[72:75], v[160:163], v[192:195], v[72:75]
	v_mfma_f32_16x16x32_bf16 v[124:127], v[156:159], v[172:175], v[124:127]
	v_mfma_f32_16x16x32_bf16 v[120:123], v[164:167], v[172:175], v[120:123]
	v_mfma_f32_16x16x32_bf16 v[108:111], v[156:159], v[180:183], v[108:111]
	v_mfma_f32_16x16x32_bf16 v[104:107], v[164:167], v[180:183], v[104:107]
	v_mfma_f32_16x16x32_bf16 v[92:95], v[156:159], v[188:191], v[92:95]
	v_mfma_f32_16x16x32_bf16 v[88:91], v[164:167], v[188:191], v[88:91]
	v_mfma_f32_16x16x32_bf16 v[76:79], v[156:159], v[196:199], v[76:79]
	v_mfma_f32_16x16x32_bf16 v[72:75], v[164:167], v[196:199], v[72:75]
	v_mfma_f32_16x16x32_bf16 v[116:119], v[200:203], v[168:171], v[116:119]
	v_mfma_f32_16x16x32_bf16 v[112:115], v[208:211], v[168:171], v[112:115]
	v_mfma_f32_16x16x32_bf16 v[100:103], v[200:203], v[176:179], v[100:103]
	v_mfma_f32_16x16x32_bf16 v[96:99], v[208:211], v[176:179], v[96:99]
	v_mfma_f32_16x16x32_bf16 v[84:87], v[200:203], v[184:187], v[84:87]
	v_mfma_f32_16x16x32_bf16 v[80:83], v[208:211], v[184:187], v[80:83]
	v_mfma_f32_16x16x32_bf16 v[68:71], v[200:203], v[192:195], v[68:71]
	v_mfma_f32_16x16x32_bf16 v[64:67], v[208:211], v[192:195], v[64:67]
	v_mfma_f32_16x16x32_bf16 v[116:119], v[204:207], v[172:175], v[116:119]
	v_mfma_f32_16x16x32_bf16 v[112:115], v[212:215], v[172:175], v[112:115]
	v_mfma_f32_16x16x32_bf16 v[100:103], v[204:207], v[180:183], v[100:103]
	v_mfma_f32_16x16x32_bf16 v[96:99], v[212:215], v[180:183], v[96:99]
	v_mfma_f32_16x16x32_bf16 v[84:87], v[204:207], v[188:191], v[84:87]
	v_mfma_f32_16x16x32_bf16 v[80:83], v[212:215], v[188:191], v[80:83]
	v_mfma_f32_16x16x32_bf16 v[68:71], v[204:207], v[196:199], v[68:71]
	v_mfma_f32_16x16x32_bf16 v[64:67], v[212:215], v[196:199], v[64:67]
	s_setprio 0
	s_barrier
	ds_read_b128 v[168:171], v154 offset:16384
	ds_read_b128 v[172:175], v154 offset:17408
	ds_read_b128 v[176:179], v154 offset:18432
	ds_read_b128 v[180:183], v154 offset:19456
	ds_read_b128 v[184:187], v154 offset:20480
	ds_read_b128 v[188:191], v154 offset:21504
	ds_read_b128 v[192:195], v154 offset:22528
	ds_read_b128 v[196:199], v154 offset:23552
	s_add_i32 s40, s65, s49
	v_lshl_add_u64 v[150:151], s[44:45], 0, v[130:131]
	s_mov_b32 m0, s40
	s_nop 0
	global_load_lds_dwordx4 v[150:151], off
	v_lshl_add_u64 v[216:217], s[44:45], 0, v[134:135]
	s_add_i32 m0, s40, 0x2000
	s_nop 0
	global_load_lds_dwordx4 v[216:217], off
	s_mov_b32 m0, s50
	v_lshl_add_u64 v[218:219], s[46:47], 0, v[128:129]
	global_load_lds_dwordx4 v[218:219], off
	v_lshl_add_u64 v[220:221], s[46:47], 0, v[132:133]
	s_mov_b32 m0, s51
	s_nop 0
	global_load_lds_dwordx4 v[220:221], off
	s_add_u32 s40, s44, 0x40000
	s_addc_u32 s41, s45, 0
	s_add_i32 s71, s66, s49
	v_lshl_add_u64 v[254:255], s[40:41], 0, v[130:131]
	s_mov_b32 m0, s71
	s_nop 0
	global_load_lds_dwordx4 v[254:255], off
	v_lshl_add_u64 v[254:255], s[40:41], 0, v[134:135]
	s_add_i32 m0, s71, 0x2000
	s_nop 0
	global_load_lds_dwordx4 v[254:255], off
	s_waitcnt vmcnt(8)
	s_waitcnt lgkmcnt(0)
	s_barrier
; #define PG8_STAGE(bufoff, gbase, voff) do { _Pragma("unroll") for (int _i = 0; _i < 2; ++_i) \
;         __builtin_amdgcn_global_load_lds((const unsigned*)((const char*)(gbase) + (voff)[_i]), (LAS unsigned*)(lds + (bufoff) + ldsw + _i * 8192), 16, 0, 0); } while (0)
; #define PG8_LDA(dst, b, h) do { _Pragma("unroll") for (int m = 0; m < 4; ++m) _Pragma("unroll") for (int k = 0; k < 2; ++k) dst[m][k] = *(const LAS bf16x8*)(lds + PG8_SA(b, h) + aoff + m * 2048 + k * 1024); } while (0)
; #define PG8_LDB(dst, b, h) do { _Pragma("unroll") for (int n = 0; n < 2; ++n) _Pragma("unroll") for (int k = 0; k < 2; ++k) dst[n][k] = *(const LAS bf16x8*)(lds + PG8_SB(b, h) + boff + n * 2048 + k * 1024); } while (0)
; #define PG8_MMA(ai, bj, At, Bt) do { __builtin_amdgcn_s_setprio(1); _Pragma("unroll") for (int m = 0; m < 4; ++m) _Pragma("unroll") for (int n = 0; n < 2; ++n) _Pragma("unroll") for (int k = 0; k < 2; ++k) \
;         acc[ai][bj][m][n] = __builtin_amdgcn_mfma_f32_16x16x32_bf16(Bt[n][k], At[m][k], acc[ai][bj][m][n], 0, 0, 0); __builtin_amdgcn_s_setprio(0); } while (0)
; #define PG8_WAIT_V(n) asm volatile("s_waitcnt vmcnt(" #n ")" ::: "memory")
; #define PG8_WAIT_L(n) asm volatile("s_waitcnt lgkmcnt(" #n ")" ::: "memory")
; #define PG8_BAR __builtin_amdgcn_s_barrier()
; #define PG8_SCHED __builtin_amdgcn_sched_barrier(0)
; template <class Epi>
; __device__ __forceinline__ void gemm_phase(LAS unsigned char* lds, const Gemm g, const StaticOrder& S, const Epi& E, int wv) {
;     ...
;             PG8_BAR; PG8_WAIT_L(0); PG8_MMA(0, 1, At, B1); PG8_BAR;
;             PG8_LDA(At, 0, 1); PG8_STAGE(PG8_SA(0, 0), a2, voffA);
;             PG8_BAR; PG8_WAIT_L(0); PG8_MMA(1, 0, At, B0); PG8_BAR; PG8_SCHED;
;             PG8_STAGE(PG8_SB(0, 1), b2 + hstep, voffB);
;             PG8_WAIT_V(6); PG8_BAR; PG8_MMA(1, 1, At, B1); PG8_BAR;
;             PG8_LDB(B0, 1, 0); PG8_SCHED; PG8_LDA(At, 1, 0); PG8_STAGE(PG8_SA(0, 1), a2 + hstep, voffA);
;             PG8_WAIT_L(8); PG8_BAR; PG8_WAIT_L(0); PG8_MMA(0, 0, At, B0); PG8_BAR; PG8_SCHED;
;             PG8_LDB(B1, 1, 1); PG8_STAGE(PG8_SB(1, 0), b3, voffB);
;             PG8_BAR; PG8_WAIT_L(0); PG8_MMA(0, 1, At, B1); PG8_BAR;
	s_setprio 1
	v_mfma_f32_16x16x32_bf16 v[60:63], v[146:149], v[168:171], v[60:63]
	v_mfma_f32_16x16x32_bf16 v[56:59], v[160:163], v[168:171], v[56:59]
	v_mfma_f32_16x16x32_bf16 v[44:47], v[146:149], v[176:179], v[44:47]
	v_mfma_f32_16x16x32_bf16 v[40:43], v[160:163], v[176:179], v[40:43]
	v_mfma_f32_16x16x32_bf16 v[28:31], v[146:149], v[184:187], v[28:31]
	v_mfma_f32_16x16x32_bf16 v[24:27], v[160:163], v[184:187], v[24:27]
	v_mfma_f32_16x16x32_bf16 v[12:15], v[146:149], v[192:195], v[12:15]
	v_mfma_f32_16x16x32_bf16 v[8:11], v[160:163], v[192:195], v[8:11]
	v_mfma_f32_16x16x32_bf16 v[60:63], v[156:159], v[172:175], v[60:63]
	v_mfma_f32_16x16x32_bf16 v[56:59], v[164:167], v[172:175], v[56:59]
	v_mfma_f32_16x16x32_bf16 v[44:47], v[156:159], v[180:183], v[44:47]
	v_mfma_f32_16x16x32_bf16 v[40:43], v[164:167], v[180:183], v[40:43]
	v_mfma_f32_16x16x32_bf16 v[28:31], v[156:159], v[188:191], v[28:31]
	v_mfma_f32_16x16x32_bf16 v[24:27], v[164:167], v[188:191], v[24:27]
	v_mfma_f32_16x16x32_bf16 v[12:15], v[156:159], v[196:199], v[12:15]
	v_mfma_f32_16x16x32_bf16 v[8:11], v[164:167], v[196:199], v[8:11]
	v_mfma_f32_16x16x32_bf16 v[52:55], v[200:203], v[168:171], v[52:55]
	v_mfma_f32_16x16x32_bf16 v[48:51], v[208:211], v[168:171], v[48:51]
	v_mfma_f32_16x16x32_bf16 v[36:39], v[200:203], v[176:179], v[36:39]
	v_mfma_f32_16x16x32_bf16 v[32:35], v[208:211], v[176:179], v[32:35]
	v_mfma_f32_16x16x32_bf16 v[20:23], v[200:203], v[184:187], v[20:23]
	v_mfma_f32_16x16x32_bf16 v[16:19], v[208:211], v[184:187], v[16:19]
	v_mfma_f32_16x16x32_bf16 v[4:7], v[200:203], v[192:195], v[4:7]
	v_mfma_f32_16x16x32_bf16 v[0:3], v[208:211], v[192:195], v[0:3]
	v_mfma_f32_16x16x32_bf16 v[52:55], v[204:207], v[172:175], v[52:55]
	v_mfma_f32_16x16x32_bf16 v[48:51], v[212:215], v[172:175], v[48:51]
	v_mfma_f32_16x16x32_bf16 v[36:39], v[204:207], v[180:183], v[36:39]
	v_mfma_f32_16x16x32_bf16 v[32:35], v[212:215], v[180:183], v[32:35]
	v_mfma_f32_16x16x32_bf16 v[20:23], v[204:207], v[188:191], v[20:23]
	v_mfma_f32_16x16x32_bf16 v[16:19], v[212:215], v[188:191], v[16:19]
	v_mfma_f32_16x16x32_bf16 v[4:7], v[204:207], v[196:199], v[4:7]
	v_mfma_f32_16x16x32_bf16 v[0:3], v[212:215], v[196:199], v[0:3]
	s_setprio 0
	s_add_i32 s71, 0, 0x18000
	v_add_u32_e32 v136, s71, v152
	s_barrier
	ds_read_b128 v[146:149], v136
	ds_read_b128 v[156:159], v136 offset:1024
	ds_read_b128 v[160:163], v136 offset:2048
	ds_read_b128 v[164:167], v136 offset:3072
	s_add_u32 s40, s46, 0x40000
	s_addc_u32 s41, s47, 0
	ds_read_b128 v[168:171], v154 offset:32768
	ds_read_b128 v[172:175], v154 offset:33792
	ds_read_b128 v[176:179], v154 offset:34816
	ds_read_b128 v[180:183], v154 offset:35840
	ds_read_b128 v[184:187], v154 offset:36864
	ds_read_b128 v[188:191], v154 offset:37888
	ds_read_b128 v[192:195], v154 offset:38912
	ds_read_b128 v[196:199], v154 offset:39936
	s_mov_b32 m0, s52
	v_lshl_add_u64 v[252:253], s[40:41], 0, v[128:129]
	global_load_lds_dwordx4 v[252:253], off
	v_lshl_add_u64 v[252:253], s[40:41], 0, v[132:133]
	s_mov_b32 m0, s53
	s_nop 0
	global_load_lds_dwordx4 v[252:253], off
	s_add_i32 s46, 0, 0x1c000
	v_add_u32_e32 v136, s46, v152
	ds_read_b128 v[200:203], v136
	ds_read_b128 v[204:207], v136 offset:1024
	ds_read_b128 v[208:211], v136 offset:2048
	ds_read_b128 v[212:215], v136 offset:3072
	s_waitcnt vmcnt(8)
	s_waitcnt lgkmcnt(0)
	s_barrier
	s_setprio 1
	v_mfma_f32_16x16x32_bf16 v[124:127], v[146:149], v[168:171], v[124:127]
	v_mfma_f32_16x16x32_bf16 v[120:123], v[160:163], v[168:171], v[120:123]
	v_mfma_f32_16x16x32_bf16 v[108:111], v[146:149], v[176:179], v[108:111]
	v_mfma_f32_16x16x32_bf16 v[104:107], v[160:163], v[176:179], v[104:107]
	v_mfma_f32_16x16x32_bf16 v[92:95], v[146:149], v[184:187], v[92:95]
	v_mfma_f32_16x16x32_bf16 v[88:91], v[160:163], v[184:187], v[88:91]
	v_mfma_f32_16x16x32_bf16 v[76:79], v[146:149], v[192:195], v[76:79]
	v_mfma_f32_16x16x32_bf16 v[72:75], v[160:163], v[192:195], v[72:75]
	v_mfma_f32_16x16x32_bf16 v[124:127], v[156:159], v[172:175], v[124:127]
	v_mfma_f32_16x16x32_bf16 v[120:123], v[164:167], v[172:175], v[120:123]
	v_mfma_f32_16x16x32_bf16 v[108:111], v[156:159], v[180:183], v[108:111]
	v_mfma_f32_16x16x32_bf16 v[104:107], v[164:167], v[180:183], v[104:107]
	v_mfma_f32_16x16x32_bf16 v[92:95], v[156:159], v[188:191], v[92:95]
	v_mfma_f32_16x16x32_bf16 v[88:91], v[164:167], v[188:191], v[88:91]
	v_mfma_f32_16x16x32_bf16 v[76:79], v[156:159], v[196:199], v[76:79]
	v_mfma_f32_16x16x32_bf16 v[72:75], v[164:167], v[196:199], v[72:75]
	v_mfma_f32_16x16x32_bf16 v[116:119], v[200:203], v[168:171], v[116:119]
	v_mfma_f32_16x16x32_bf16 v[112:115], v[208:211], v[168:171], v[112:115]
	v_mfma_f32_16x16x32_bf16 v[100:103], v[200:203], v[176:179], v[100:103]
	v_mfma_f32_16x16x32_bf16 v[96:99], v[208:211], v[176:179], v[96:99]
	v_mfma_f32_16x16x32_bf16 v[84:87], v[200:203], v[184:187], v[84:87]
	v_mfma_f32_16x16x32_bf16 v[80:83], v[208:211], v[184:187], v[80:83]
	v_mfma_f32_16x16x32_bf16 v[68:71], v[200:203], v[192:195], v[68:71]
	v_mfma_f32_16x16x32_bf16 v[64:67], v[208:211], v[192:195], v[64:67]
	v_mfma_f32_16x16x32_bf16 v[116:119], v[204:207], v[172:175], v[116:119]
	v_mfma_f32_16x16x32_bf16 v[112:115], v[212:215], v[172:175], v[112:115]
	v_mfma_f32_16x16x32_bf16 v[100:103], v[204:207], v[180:183], v[100:103]
	v_mfma_f32_16x16x32_bf16 v[96:99], v[212:215], v[180:183], v[96:99]
	v_mfma_f32_16x16x32_bf16 v[84:87], v[204:207], v[188:191], v[84:87]
	v_mfma_f32_16x16x32_bf16 v[80:83], v[212:215], v[188:191], v[80:83]
	v_mfma_f32_16x16x32_bf16 v[68:71], v[204:207], v[196:199], v[68:71]
	v_mfma_f32_16x16x32_bf16 v[64:67], v[212:215], v[196:199], v[64:67]
	s_setprio 0
	s_barrier
; #define PG8_STAGE(bufoff, gbase, voff) do { _Pragma("unroll") for (int _i = 0; _i < 2; ++_i) \
;         __builtin_amdgcn_global_load_lds((const unsigned*)((const char*)(gbase) + (voff)[_i]), (LAS unsigned*)(lds + (bufoff) + ldsw + _i * 8192), 16, 0, 0); } while (0)
; #define PG8_LDA(dst, b, h) do { _Pragma("unroll") for (int m = 0; m < 4; ++m) _Pragma("unroll") for (int k = 0; k < 2; ++k) dst[m][k] = *(const LAS bf16x8*)(lds + PG8_SA(b, h) + aoff + m * 2048 + k * 1024); } while (0)
; #define PG8_MMA(ai, bj, At, Bt) do { __builtin_amdgcn_s_setprio(1); _Pragma("unroll") for (int m = 0; m < 4; ++m) _Pragma("unroll") for (int n = 0; n < 2; ++n) _Pragma("unroll") for (int k = 0; k < 2; ++k) \
;         acc[ai][bj][m][n] = __builtin_amdgcn_mfma_f32_16x16x32_bf16(Bt[n][k], At[m][k], acc[ai][bj][m][n], 0, 0, 0); __builtin_amdgcn_s_setprio(0); } while (0)
; #define PG8_WAIT_V(n) asm volatile("s_waitcnt vmcnt(" #n ")" ::: "memory")
; #define PG8_BAR __builtin_amdgcn_s_barrier()
; template <class Epi>
; __device__ __forceinline__ void gemm_phase(LAS unsigned char* lds, const Gemm g, const StaticOrder& S, const Epi& E, int wv) {
;     ...
;             PG8_LDA(At, 1, 1); PG8_STAGE(PG8_SA(1, 0), a3, voffA);
;             PG8_BAR; PG8_WAIT_L(0); PG8_MMA(1, 0, At, B0); PG8_BAR; PG8_SCHED;
;             PG8_STAGE(PG8_SB(1, 1), b3 + hstep, voffB);
;             PG8_WAIT_V(6); PG8_BAR; PG8_MMA(1, 1, At, B1); PG8_BAR;
;     __device__ __forceinline__ void operator()(const f32x4 (&acc)[2][2][4][2], const Unit& u, int wr, int wc, int fr, int fq) const {
;         const bool latent = u.pm < 128;
; #pragma unroll
;         for (int ai = 0; ai < 2; ++ai)
; #pragma unroll
;             for (int m = 0; m < 4; ++m) {
;                 const int row = u.pm * 256 + ai * 128 + wr * 64 + 4 * fr + m;
;                 const int t = row & (S - 1);
;                 const int pos = (wc & 1) ? (t & 63) : (t >> 6);
; #pragma unroll
;                 for (int bj = 0; bj < 2; ++bj) {
;                     const int col = u.pn * 256 + bj * 128 + wc * 32 + 4 * fq;
;                     f32x4 v0 = acc[ai][bj][m][0], v1 = acc[ai][bj][m][1];
;                     const bool rope = latent && (u.pn == 4 || u.pn == 5 || (u.pn == 6 && bj == 0));
;                     if (rope) {
;                         const f32x4 cs = *(const f32x4*)(cosT + pos * 16 + 4 * fq), sn = *(const f32x4*)(sinT + pos * 16 + 4 * fq);
	ds_read_b128 v[168:171], v154 offset:49152
	ds_read_b128 v[172:175], v154 offset:50176
	ds_read_b128 v[176:179], v154 offset:51200
	ds_read_b128 v[180:183], v154 offset:52224
	ds_read_b128 v[184:187], v154 offset:53248
	ds_read_b128 v[188:191], v154 offset:54272
	ds_read_b128 v[192:195], v154 offset:55296
	ds_read_b128 v[196:199], v154 offset:56320
	s_add_i32 s40, s71, s49
	v_lshl_add_u64 v[150:151], v[150:151], 0, s[28:29]
	s_mov_b32 m0, s40
	s_nop 0
	global_load_lds_dwordx4 v[150:151], off
	v_lshl_add_u64 v[150:151], v[216:217], 0, s[28:29]
	s_add_i32 m0, s40, 0x2000
	s_nop 0
	global_load_lds_dwordx4 v[150:151], off
	s_mov_b32 m0, s58
	v_lshl_add_u64 v[150:151], v[218:219], 0, s[28:29]
	global_load_lds_dwordx4 v[150:151], off
	v_lshl_add_u64 v[150:151], v[220:221], 0, s[28:29]
	s_mov_b32 m0, s59
	s_nop 0
	global_load_lds_dwordx4 v[150:151], off
	s_add_u32 s40, s44, 0x40080
	s_addc_u32 s41, s45, 0
	s_add_i32 s44, s46, s49
	v_lshl_add_u64 v[254:255], s[40:41], 0, v[130:131]
	s_mov_b32 m0, s44
	s_nop 0
	global_load_lds_dwordx4 v[254:255], off
	v_lshl_add_u64 v[254:255], s[40:41], 0, v[134:135]
	s_add_i32 m0, s44, 0x2000
	s_nop 0
	global_load_lds_dwordx4 v[254:255], off
	s_waitcnt vmcnt(8)
	s_waitcnt lgkmcnt(0)
	s_barrier
	s_setprio 1
	v_mfma_f32_16x16x32_bf16 v[60:63], v[146:149], v[168:171], v[60:63]
	v_mfma_f32_16x16x32_bf16 v[56:59], v[160:163], v[168:171], v[56:59]
	v_mfma_f32_16x16x32_bf16 v[44:47], v[146:149], v[176:179], v[44:47]
	v_mfma_f32_16x16x32_bf16 v[40:43], v[160:163], v[176:179], v[40:43]
	v_mfma_f32_16x16x32_bf16 v[28:31], v[146:149], v[184:187], v[28:31]
	v_mfma_f32_16x16x32_bf16 v[24:27], v[160:163], v[184:187], v[24:27]
	v_mfma_f32_16x16x32_bf16 v[12:15], v[146:149], v[192:195], v[12:15]
	v_mfma_f32_16x16x32_bf16 v[8:11], v[160:163], v[192:195], v[8:11]
	v_mfma_f32_16x16x32_bf16 v[60:63], v[156:159], v[172:175], v[60:63]
	v_mfma_f32_16x16x32_bf16 v[56:59], v[164:167], v[172:175], v[56:59]
	v_mfma_f32_16x16x32_bf16 v[44:47], v[156:159], v[180:183], v[44:47]
	v_mfma_f32_16x16x32_bf16 v[40:43], v[164:167], v[180:183], v[40:43]
	v_mfma_f32_16x16x32_bf16 v[28:31], v[156:159], v[188:191], v[28:31]
	v_mfma_f32_16x16x32_bf16 v[24:27], v[164:167], v[188:191], v[24:27]
	v_mfma_f32_16x16x32_bf16 v[12:15], v[156:159], v[196:199], v[12:15]
	v_mfma_f32_16x16x32_bf16 v[8:11], v[164:167], v[196:199], v[8:11]
	v_mfma_f32_16x16x32_bf16 v[52:55], v[200:203], v[168:171], v[52:55]
	v_mfma_f32_16x16x32_bf16 v[48:51], v[208:211], v[168:171], v[48:51]
	v_mfma_f32_16x16x32_bf16 v[36:39], v[200:203], v[176:179], v[36:39]
	v_mfma_f32_16x16x32_bf16 v[32:35], v[208:211], v[176:179], v[32:35]
	v_mfma_f32_16x16x32_bf16 v[20:23], v[200:203], v[184:187], v[20:23]
	v_mfma_f32_16x16x32_bf16 v[16:19], v[208:211], v[184:187], v[16:19]
	v_mfma_f32_16x16x32_bf16 v[4:7], v[200:203], v[192:195], v[4:7]
	v_mfma_f32_16x16x32_bf16 v[0:3], v[208:211], v[192:195], v[0:3]
	v_mfma_f32_16x16x32_bf16 v[52:55], v[204:207], v[172:175], v[52:55]
	v_mfma_f32_16x16x32_bf16 v[48:51], v[212:215], v[172:175], v[48:51]
	v_mfma_f32_16x16x32_bf16 v[36:39], v[204:207], v[180:183], v[36:39]
	v_mfma_f32_16x16x32_bf16 v[32:35], v[212:215], v[180:183], v[32:35]
	v_mfma_f32_16x16x32_bf16 v[20:23], v[204:207], v[188:191], v[20:23]
	v_mfma_f32_16x16x32_bf16 v[16:19], v[212:215], v[188:191], v[16:19]
	v_mfma_f32_16x16x32_bf16 v[4:7], v[204:207], v[196:199], v[4:7]
	v_mfma_f32_16x16x32_bf16 v[0:3], v[212:215], v[196:199], v[0:3]
	s_setprio 0
	s_add_i32 s70, s70, 2
	s_add_u32 s68, s68, 0x100
	s_addc_u32 s69, s69, 0
	s_cmp_gt_u32 s70, 13
	s_mov_b64 s[40:41], s[42:43]
	s_barrier
	s_cbranch_scc0 .LBB0_215
	s_cmpk_lt_i32 s6, 0x80
	s_cselect_b64 s[40:41], -1, 0
	s_lshl_b32 s31, s6, 8
	s_add_i32 s31, s31, s55
	s_mov_b32 s7, -1
	v_mbcnt_lo_u32_b32 v136, s7, 0
	v_mbcnt_hi_u32_b32 v136, s7, v136
	s_add_i32 s6, s8, -4
	s_cmp_lt_u32 s6, 3
	s_cselect_b64 s[6:7], -1, 0
	s_and_b64 s[42:43], s[40:41], s[6:7]
	s_and_b32 s9, s8, -2
	s_cmp_eq_u32 s9, 4
	s_cselect_b64 s[6:7], -1, 0
	s_and_b64 s[40:41], s[40:41], s[6:7]
	v_lshlrev_b32_e32 v146, 2, v136
	v_and_b32_e32 v156, 60, v146
	v_lshrrev_b32_e32 v147, 2, v136
	v_and_b32_e32 v148, 28, v147
	v_bfe_u32 v222, v136, 5, 1
	v_bfe_u32 v223, v136, 4, 1
	v_lshlrev_b32_e32 v222, 4, v222
	v_lshl_or_b32 v222, v223, 5, v222
	s_lshl_b32 s9, s8, 8
	s_or_b32 s9, s9, s57
	s_lshl_b32 s9, s9, 1
	v_add_u32_e32 v222, s9, v222
	v_or_b32_e32 v157, s31, v156
	v_mul_lo_u32 v150, v157, s67
	v_add_u32_e32 v150, v150, v222
	v_mov_b32_e32 v151, 0
	v_lshl_add_u64 v[224:225], s[18:19], 0, v[150:151]
	s_mov_b64 s[6:7], 0x1c00
	v_lshl_add_u64 v[226:227], v[224:225], 0, s[6:7]
	s_mov_b64 s[6:7], 0x70000
	v_lshl_add_u64 v[228:229], v[224:225], 0, s[6:7]
	s_mov_b64 s[6:7], 0x71c00
	v_lshl_add_u64 v[230:231], v[224:225], 0, s[6:7]
	s_and_b64 vcc, exec, s[42:43]
	s_cbranch_vccz .Lproj_norope
	s_bfe_u32 s35, s31, 0x80006
	s_add_i32 s9, s31, 0x80
	s_bfe_u32 s9, s9, 0x80006
	v_lshlrev_b32_e32 v232, 2, v148
	v_mov_b32_e32 v234, s35
	v_cndmask_b32_e64 v240, v156, v234, s[10:11]
	v_lshl_add_u32 v240, v240, 6, v232
	global_load_dwordx4 v[158:161], v240, s[22:23]
	global_load_dwordx4 v[162:165], v240, s[20:21]
	v_or_b32_e32 v241, 1, v156
	v_cndmask_b32_e64 v241, v241, v234, s[10:11]
	v_lshl_add_u32 v241, v241, 6, v232
	global_load_dwordx4 v[166:169], v241, s[22:23]
	global_load_dwordx4 v[170:173], v241, s[20:21]
	v_or_b32_e32 v242, 2, v156
	v_cndmask_b32_e64 v242, v242, v234, s[10:11]
	v_lshl_add_u32 v242, v242, 6, v232
	global_load_dwordx4 v[174:177], v242, s[22:23]
	global_load_dwordx4 v[178:181], v242, s[20:21]
	v_or_b32_e32 v243, 3, v156
	v_cndmask_b32_e64 v243, v243, v234, s[10:11]
	v_lshl_add_u32 v243, v243, 6, v232
	global_load_dwordx4 v[182:185], v243, s[22:23]
	global_load_dwordx4 v[186:189], v243, s[20:21]
	v_mov_b32_e32 v234, s9
	v_cndmask_b32_e64 v244, v156, v234, s[10:11]
	v_lshl_add_u32 v244, v244, 6, v232
	global_load_dwordx4 v[190:193], v244, s[22:23]
	global_load_dwordx4 v[194:197], v244, s[20:21]
	v_or_b32_e32 v245, 1, v156
	v_cndmask_b32_e64 v245, v245, v234, s[10:11]
	v_lshl_add_u32 v245, v245, 6, v232
	global_load_dwordx4 v[198:201], v245, s[22:23]
	global_load_dwordx4 v[202:205], v245, s[20:21]
	v_or_b32_e32 v246, 2, v156
	v_cndmask_b32_e64 v246, v246, v234, s[10:11]
	v_lshl_add_u32 v246, v246, 6, v232
	global_load_dwordx4 v[206:209], v246, s[22:23]
	global_load_dwordx4 v[210:213], v246, s[20:21]
	v_or_b32_e32 v247, 3, v156
	v_cndmask_b32_e64 v247, v247, v234, s[10:11]
	v_lshl_add_u32 v247, v247, 6, v232
	global_load_dwordx4 v[214:217], v247, s[22:23]
	global_load_dwordx4 v[218:221], v247, s[20:21]
	s_waitcnt vmcnt(0)

; #define PG8_STAGE(bufoff, gbase, voff) do { _Pragma("unroll") for (int _i = 0; _i < 2; ++_i) \
;         __builtin_amdgcn_global_load_lds((const unsigned*)((const char*)(gbase) + (voff)[_i]), (LAS unsigned*)(lds + (bufoff) + ldsw + _i * 8192), 16, 0, 0); } while (0)
; #define PG8_WAIT_V(n) asm volatile("s_waitcnt vmcnt(" #n ")" ::: "memory")
; #define PG8_BAR __builtin_amdgcn_s_barrier()
; template <class Epi>
; __device__ __forceinline__ void gemm_phase(LAS unsigned char* lds, const Gemm g, const StaticOrder& S, const Epi& E, int wv) {
;     ...
;     const char* cA = (const char*)g.A + (size_t)cur.pm * tstepA; const char* cB = (const char*)g.Bt + (size_t)cur.pn * tstepB;
;     PG8_STAGE(PG8_SB(0, 0), cB, voffB); PG8_STAGE(PG8_SA(0, 0), cA, voffA); PG8_STAGE(PG8_SB(0, 1), cB + hstep, voffB); PG8_STAGE(PG8_SA(0, 1), cA + hstep, voffA);
;     if (wr == 1) PG8_BAR;
;     PG8_WAIT_V(4); PG8_BAR;
;     PG8_STAGE(PG8_SB(1, 0), cB + kstep, voffB); PG8_STAGE(PG8_SA(1, 0), cA + kstep, voffA); PG8_STAGE(PG8_SB(1, 1), cB + hstep + kstep, voffB);
;     PG8_WAIT_V(6); PG8_BAR;
.LBB0_838:
	s_add_u32 s14, s6, 0xcc77000
	s_addc_u32 s15, s7, 0
	s_lshl_b32 s5, s5, 5
	s_mov_b64 s[16:17], 0x80
	s_and_b32 s66, s5, 0x60
	s_add_i32 m0, s59, 0x18000
	v_lshl_add_u64 v[6:7], v[6:7], 0, s[16:17]
	s_lshl_b32 s65, s8, 6
	s_lshl_b32 s20, s8, 13
	s_lshl_b32 s5, s66, 7
	s_waitcnt vmcnt(2)
	s_barrier
	global_load_lds_dwordx4 v[6:7], off
	v_lshl_add_u64 v[4:5], v[4:5], 0, s[16:17]
	s_add_i32 m0, s59, 0x1a000
	s_add_i32 s67, s59, 0x8000
	s_add_i32 s68, s59, 0xa000
	global_load_lds_dwordx4 v[4:5], off
	v_lshl_add_u64 v[2:3], v[2:3], 0, s[16:17]
	s_mov_b32 m0, s67
	s_add_u32 s18, s46, 0x40080
	global_load_lds_dwordx4 v[2:3], off
	v_lshl_add_u64 v[0:1], v[0:1], 0, s[16:17]
	s_mov_b32 m0, s68
	s_addc_u32 s19, s47, 0
	global_load_lds_dwordx4 v[0:1], off
	s_add_i32 m0, s59, 0x1c000
	v_lshl_add_u64 v[0:1], s[18:19], 0, v[146:147]
	global_load_lds_dwordx4 v[0:1], off
	v_lshl_add_u64 v[0:1], s[18:19], 0, v[150:151]
	s_add_i32 m0, s59, 0x1e000
	s_sext_i32_i8 s8, s4
	global_load_lds_dwordx4 v[0:1], off
	v_and_b32_e32 v0, 15, v8
	v_and_b32_e32 v1, 48, v8
	v_lshl_or_b32 v0, v0, 6, v1
	v_lshlrev_b32_e32 v1, 2, v8
	v_and_b32_e32 v1, 32, v1
	v_bitop3_b32 v2, v0, s20, v1 bitop3:0xde
	v_bitop3_b32 v164, s5, v0, v1 bitop3:0xf6
	v_and_b32_e32 v1, 1, v9
	v_add3_u32 v0, v11, v12, v13
	v_lshlrev_b32_e32 v1, 6, v1
	v_lshl_or_b32 v0, v0, 11, v1
	v_and_b32_e32 v1, 1, v14
	v_lshl_add_u32 v152, v10, 1, v0
	v_add3_u32 v0, v16, v17, v18
	v_lshlrev_b32_e32 v1, 6, v1
	s_mov_b64 s[4:5], 0x40080
	s_waitcnt vmcnt(6)
	v_lshl_or_b32 v0, v0, 11, v1
	v_lshl_add_u64 v[154:155], v[152:153], 0, s[4:5]
	v_lshl_add_u32 v152, v15, 1, v0
	s_add_i32 s72, 0, 0x10000
	s_add_i32 s73, 0, 0x14000
	s_ashr_i32 s69, s65, 31
	s_ashr_i32 s70, s24, 31
	s_mov_b32 s71, s24
	v_lshl_add_u64 v[156:157], v[152:153], 0, s[4:5]
	v_mov_b64_e32 v[158:159], 0x200
	v_mov_b64_e32 v[160:161], 0x1ff
	v_add_u32_e32 v165, s72, v164
	v_add_u32_e32 v166, 0, v2
	v_add_u32_e32 v167, s73, v164
	s_mov_b32 s74, 0x1648000
	s_mov_b64 s[18:19], 0x1000
	s_movk_i32 s75, 0x1000
	s_mov_b64 s[20:21], 0x1800
	s_mov_b32 s76, 0x40000
	s_mov_b64 s[22:23], 0x40800
	s_mov_b64 s[28:29], 0x41000
	s_mov_b32 s77, 0x41000
	s_mov_b64 s[30:31], 0x41800
	s_mov_b32 s78, 0
	s_barrier

; #define PG8_STAGE(bufoff, gbase, voff) do { _Pragma("unroll") for (int _i = 0; _i < 2; ++_i) \
;         __builtin_amdgcn_global_load_lds((const unsigned*)((const char*)(gbase) + (voff)[_i]), (LAS unsigned*)(lds + (bufoff) + ldsw + _i * 8192), 16, 0, 0); } while (0)
; #define PG8_LDA(dst, b, h) do { _Pragma("unroll") for (int m = 0; m < 4; ++m) _Pragma("unroll") for (int k = 0; k < 2; ++k) dst[m][k] = *(const LAS bf16x8*)(lds + PG8_SA(b, h) + aoff + m * 2048 + k * 1024); } while (0)
; #define PG8_LDB(dst, b, h) do { _Pragma("unroll") for (int n = 0; n < 2; ++n) _Pragma("unroll") for (int k = 0; k < 2; ++k) dst[n][k] = *(const LAS bf16x8*)(lds + PG8_SB(b, h) + boff + n * 2048 + k * 1024); } while (0)
; #define PG8_MMA(ai, bj, At, Bt) do { __builtin_amdgcn_s_setprio(1); _Pragma("unroll") for (int m = 0; m < 4; ++m) _Pragma("unroll") for (int n = 0; n < 2; ++n) _Pragma("unroll") for (int k = 0; k < 2; ++k) \
;         acc[ai][bj][m][n] = __builtin_amdgcn_mfma_f32_16x16x32_bf16(Bt[n][k], At[m][k], acc[ai][bj][m][n], 0, 0, 0); __builtin_amdgcn_s_setprio(0); } while (0)
; #define PG8_WAIT_V(n) asm volatile("s_waitcnt vmcnt(" #n ")" ::: "memory")
; #define PG8_WAIT_L(n) asm volatile("s_waitcnt lgkmcnt(" #n ")" ::: "memory")
; #define PG8_BAR __builtin_amdgcn_s_barrier()
; #define PG8_SCHED __builtin_amdgcn_sched_barrier(0)
; template <class Epi>
; __device__ __forceinline__ void gemm_phase(LAS unsigned char* lds, const Gemm g, const StaticOrder& S, const Epi& E, int wv) {
;     ...
;             PG8_LDB(B0, 0, 0); PG8_SCHED; PG8_LDA(At, 0, 0); PG8_STAGE(PG8_SA(1, 1), a1 + hstep, voffA);
;             PG8_WAIT_L(8); PG8_BAR; PG8_WAIT_L(0); PG8_MMA(0, 0, At, B0); PG8_BAR; PG8_SCHED;
;             PG8_LDB(B1, 0, 1); PG8_STAGE(PG8_SB(0, 0), b2, voffB);
;             PG8_BAR; PG8_WAIT_L(0); PG8_MMA(0, 1, At, B1); PG8_BAR;
;             PG8_LDA(At, 0, 1); PG8_STAGE(PG8_SA(0, 0), a2, voffA);
;             PG8_BAR; PG8_WAIT_L(0); PG8_MMA(1, 0, At, B0); PG8_BAR; PG8_SCHED;
;             PG8_STAGE(PG8_SB(0, 1), b2 + hstep, voffB);
;             PG8_WAIT_V(6); PG8_BAR; PG8_MMA(1, 1, At, B1); PG8_BAR;
.LBB0_846:
	ds_read_b128 v[128:131], v165
	ds_read_b128 v[132:135], v165 offset:1024
	ds_read_b128 v[136:139], v165 offset:2048
	ds_read_b128 v[140:143], v165 offset:3072
	s_add_u32 s46, s44, 0x100
	s_addc_u32 s47, s45, 0
	s_cmp_eq_u32 s82, 12
	s_cselect_b32 s51, s37, s47
	s_cselect_b32 s50, s43, s46
	s_cselect_b32 s49, s35, s81
	s_cselect_b32 s48, s79, s80
	ds_read_b128 v[168:171], v166
	ds_read_b128 v[172:175], v166 offset:1024
	ds_read_b128 v[176:179], v166 offset:2048
	ds_read_b128 v[180:183], v166 offset:3072
	ds_read_b128 v[184:187], v166 offset:4096
	ds_read_b128 v[188:191], v166 offset:5120
	ds_read_b128 v[192:195], v166 offset:6144
	ds_read_b128 v[196:199], v166 offset:7168
	ds_read_b128 v[200:203], v167
	ds_read_b128 v[204:207], v167 offset:1024
	ds_read_b128 v[208:211], v167 offset:2048
	ds_read_b128 v[212:215], v167 offset:3072
	v_lshl_add_u64 v[252:253], s[44:45], 0, v[154:155]
	s_add_i32 m0, s59, 0xc000
	s_nop 0
	global_load_lds_dwordx4 v[252:253], off
	v_lshl_add_u64 v[252:253], s[44:45], 0, v[156:157]
	s_add_i32 m0, s59, 0xe000
	s_nop 0
	global_load_lds_dwordx4 v[252:253], off
	s_waitcnt vmcnt(8)
	s_waitcnt lgkmcnt(0)
	s_barrier
	s_setprio 1
	v_mfma_f32_16x16x32_bf16 v[124:127], v[128:131], v[168:171], v[124:127]
	v_mfma_f32_16x16x32_bf16 v[120:123], v[136:139], v[168:171], v[120:123]
	v_mfma_f32_16x16x32_bf16 v[116:119], v[128:131], v[176:179], v[116:119]
	v_mfma_f32_16x16x32_bf16 v[112:115], v[136:139], v[176:179], v[112:115]
	v_mfma_f32_16x16x32_bf16 v[108:111], v[128:131], v[184:187], v[108:111]
	v_mfma_f32_16x16x32_bf16 v[96:99], v[136:139], v[184:187], v[96:99]
	v_mfma_f32_16x16x32_bf16 v[80:83], v[128:131], v[192:195], v[80:83]
	v_mfma_f32_16x16x32_bf16 v[72:75], v[136:139], v[192:195], v[72:75]
	v_mfma_f32_16x16x32_bf16 v[124:127], v[132:135], v[172:175], v[124:127]
	v_mfma_f32_16x16x32_bf16 v[120:123], v[140:143], v[172:175], v[120:123]
	v_mfma_f32_16x16x32_bf16 v[116:119], v[132:135], v[180:183], v[116:119]
	v_mfma_f32_16x16x32_bf16 v[112:115], v[140:143], v[180:183], v[112:115]
	v_mfma_f32_16x16x32_bf16 v[108:111], v[132:135], v[188:191], v[108:111]
	v_mfma_f32_16x16x32_bf16 v[96:99], v[140:143], v[188:191], v[96:99]
	v_mfma_f32_16x16x32_bf16 v[80:83], v[132:135], v[196:199], v[80:83]
	v_mfma_f32_16x16x32_bf16 v[72:75], v[140:143], v[196:199], v[72:75]
	v_mfma_f32_16x16x32_bf16 v[104:107], v[200:203], v[168:171], v[104:107]
	v_mfma_f32_16x16x32_bf16 v[100:103], v[208:211], v[168:171], v[100:103]
	v_mfma_f32_16x16x32_bf16 v[92:95], v[200:203], v[176:179], v[92:95]
	v_mfma_f32_16x16x32_bf16 v[88:91], v[208:211], v[176:179], v[88:91]
	v_mfma_f32_16x16x32_bf16 v[84:87], v[200:203], v[184:187], v[84:87]
	v_mfma_f32_16x16x32_bf16 v[76:79], v[208:211], v[184:187], v[76:79]
	v_mfma_f32_16x16x32_bf16 v[68:71], v[200:203], v[192:195], v[68:71]
	v_mfma_f32_16x16x32_bf16 v[64:67], v[208:211], v[192:195], v[64:67]
	v_mfma_f32_16x16x32_bf16 v[104:107], v[204:207], v[172:175], v[104:107]
	v_mfma_f32_16x16x32_bf16 v[100:103], v[212:215], v[172:175], v[100:103]
	v_mfma_f32_16x16x32_bf16 v[92:95], v[204:207], v[180:183], v[92:95]
	v_mfma_f32_16x16x32_bf16 v[88:91], v[212:215], v[180:183], v[88:91]
	v_mfma_f32_16x16x32_bf16 v[84:87], v[204:207], v[188:191], v[84:87]
	v_mfma_f32_16x16x32_bf16 v[76:79], v[212:215], v[188:191], v[76:79]
	v_mfma_f32_16x16x32_bf16 v[68:71], v[204:207], v[196:199], v[68:71]
	v_mfma_f32_16x16x32_bf16 v[64:67], v[212:215], v[196:199], v[64:67]
	s_setprio 0
	s_barrier
	ds_read_b128 v[168:171], v166 offset:16384
	ds_read_b128 v[172:175], v166 offset:17408
	ds_read_b128 v[176:179], v166 offset:18432
	ds_read_b128 v[180:183], v166 offset:19456
	ds_read_b128 v[184:187], v166 offset:20480
	ds_read_b128 v[188:191], v166 offset:21504
	ds_read_b128 v[192:195], v166 offset:22528
	ds_read_b128 v[196:199], v166 offset:23552
	s_add_i32 s44, s72, s58
	v_lshl_add_u64 v[162:163], s[48:49], 0, v[146:147]
	s_mov_b32 m0, s44
	s_nop 0
	global_load_lds_dwordx4 v[162:163], off
	v_lshl_add_u64 v[216:217], s[48:49], 0, v[150:151]
	s_add_i32 m0, s44, 0x2000
	s_nop 0
	global_load_lds_dwordx4 v[216:217], off
	s_mov_b32 m0, s59
	v_lshl_add_u64 v[218:219], s[50:51], 0, v[144:145]
	global_load_lds_dwordx4 v[218:219], off
	v_lshl_add_u64 v[220:221], s[50:51], 0, v[148:149]
	s_mov_b32 m0, s60
	s_nop 0
	global_load_lds_dwordx4 v[220:221], off
	s_add_u32 s44, s48, 0x40000
	s_addc_u32 s45, s49, 0
	s_add_i32 s83, s73, s58
	v_lshl_add_u64 v[254:255], s[44:45], 0, v[146:147]
	s_mov_b32 m0, s83
	s_nop 0
	global_load_lds_dwordx4 v[254:255], off
	v_lshl_add_u64 v[254:255], s[44:45], 0, v[150:151]
	s_add_i32 m0, s83, 0x2000
	s_nop 0
	global_load_lds_dwordx4 v[254:255], off
	s_waitcnt vmcnt(8)
	s_waitcnt lgkmcnt(0)
	s_barrier
; #define PG8_STAGE(bufoff, gbase, voff) do { _Pragma("unroll") for (int _i = 0; _i < 2; ++_i) \
;         __builtin_amdgcn_global_load_lds((const unsigned*)((const char*)(gbase) + (voff)[_i]), (LAS unsigned*)(lds + (bufoff) + ldsw + _i * 8192), 16, 0, 0); } while (0)
; #define PG8_LDA(dst, b, h) do { _Pragma("unroll") for (int m = 0; m < 4; ++m) _Pragma("unroll") for (int k = 0; k < 2; ++k) dst[m][k] = *(const LAS bf16x8*)(lds + PG8_SA(b, h) + aoff + m * 2048 + k * 1024); } while (0)
; #define PG8_LDB(dst, b, h) do { _Pragma("unroll") for (int n = 0; n < 2; ++n) _Pragma("unroll") for (int k = 0; k < 2; ++k) dst[n][k] = *(const LAS bf16x8*)(lds + PG8_SB(b, h) + boff + n * 2048 + k * 1024); } while (0)
; #define PG8_WAIT_V(n) asm volatile("s_waitcnt vmcnt(" #n ")" ::: "memory")
; #define PG8_WAIT_L(n) asm volatile("s_waitcnt lgkmcnt(" #n ")" ::: "memory")
; #define PG8_BAR __builtin_amdgcn_s_barrier()
; #define PG8_SCHED __builtin_amdgcn_sched_barrier(0)
; template <class Epi>
; __device__ __forceinline__ void gemm_phase(LAS unsigned char* lds, const Gemm g, const StaticOrder& S, const Epi& E, int wv) {
;     ...
;             PG8_LDB(B0, 0, 0); PG8_SCHED; PG8_LDA(At, 0, 0); PG8_STAGE(PG8_SA(1, 1), a1 + hstep, voffA);
;             PG8_WAIT_L(8); PG8_BAR; PG8_WAIT_L(0); PG8_MMA(0, 0, At, B0); PG8_BAR; PG8_SCHED;
;             PG8_LDB(B1, 0, 1); PG8_STAGE(PG8_SB(0, 0), b2, voffB);
;             PG8_BAR; PG8_WAIT_L(0); PG8_MMA(0, 1, At, B1); PG8_BAR;
;             PG8_LDA(At, 0, 1); PG8_STAGE(PG8_SA(0, 0), a2, voffA);
;             PG8_BAR; PG8_WAIT_L(0); PG8_MMA(1, 0, At, B0); PG8_BAR; PG8_SCHED;
;             PG8_STAGE(PG8_SB(0, 1), b2 + hstep, voffB);
;             PG8_WAIT_V(6); PG8_BAR; PG8_MMA(1, 1, At, B1); PG8_BAR;
;             PG8_LDB(B0, 1, 0); PG8_SCHED; PG8_LDA(At, 1, 0); PG8_STAGE(PG8_SA(0, 1), a2 + hstep, voffA);
;             PG8_WAIT_L(8); PG8_BAR; PG8_WAIT_L(0); PG8_MMA(0, 0, At, B0); PG8_BAR; PG8_SCHED;
;             PG8_LDB(B1, 1, 1); PG8_STAGE(PG8_SB(1, 0), b3, voffB);
;             PG8_BAR; PG8_WAIT_L(0); PG8_MMA(0, 1, At, B1); PG8_BAR;
;             PG8_LDA(At, 1, 1); PG8_STAGE(PG8_SA(1, 0), a3, voffA);
;             PG8_BAR; PG8_WAIT_L(0); PG8_MMA(1, 0, At, B0); PG8_BAR; PG8_SCHED;
;             PG8_STAGE(PG8_SB(1, 1), b3 + hstep, voffB);
;             PG8_WAIT_V(6); PG8_BAR; PG8_MMA(1, 1, At, B1); PG8_BAR;
	s_setprio 1
	v_mfma_f32_16x16x32_bf16 v[60:63], v[128:131], v[168:171], v[60:63]
	v_mfma_f32_16x16x32_bf16 v[56:59], v[136:139], v[168:171], v[56:59]
	v_mfma_f32_16x16x32_bf16 v[48:51], v[128:131], v[176:179], v[48:51]
	v_mfma_f32_16x16x32_bf16 v[40:43], v[136:139], v[176:179], v[40:43]
	v_mfma_f32_16x16x32_bf16 v[32:35], v[128:131], v[184:187], v[32:35]
	v_mfma_f32_16x16x32_bf16 v[24:27], v[136:139], v[184:187], v[24:27]
	v_mfma_f32_16x16x32_bf16 v[16:19], v[128:131], v[192:195], v[16:19]
	v_mfma_f32_16x16x32_bf16 v[8:11], v[136:139], v[192:195], v[8:11]
	v_mfma_f32_16x16x32_bf16 v[60:63], v[132:135], v[172:175], v[60:63]
	v_mfma_f32_16x16x32_bf16 v[56:59], v[140:143], v[172:175], v[56:59]
	v_mfma_f32_16x16x32_bf16 v[48:51], v[132:135], v[180:183], v[48:51]
	v_mfma_f32_16x16x32_bf16 v[40:43], v[140:143], v[180:183], v[40:43]
	v_mfma_f32_16x16x32_bf16 v[32:35], v[132:135], v[188:191], v[32:35]
	v_mfma_f32_16x16x32_bf16 v[24:27], v[140:143], v[188:191], v[24:27]
	v_mfma_f32_16x16x32_bf16 v[16:19], v[132:135], v[196:199], v[16:19]
	v_mfma_f32_16x16x32_bf16 v[8:11], v[140:143], v[196:199], v[8:11]
	v_mfma_f32_16x16x32_bf16 v[52:55], v[200:203], v[168:171], v[52:55]
	v_mfma_f32_16x16x32_bf16 v[44:47], v[208:211], v[168:171], v[44:47]
	v_mfma_f32_16x16x32_bf16 v[36:39], v[200:203], v[176:179], v[36:39]
	v_mfma_f32_16x16x32_bf16 v[28:31], v[208:211], v[176:179], v[28:31]
	v_mfma_f32_16x16x32_bf16 v[20:23], v[200:203], v[184:187], v[20:23]
	v_mfma_f32_16x16x32_bf16 v[12:15], v[208:211], v[184:187], v[12:15]
	v_mfma_f32_16x16x32_bf16 v[4:7], v[200:203], v[192:195], v[4:7]
	v_mfma_f32_16x16x32_bf16 v[0:3], v[208:211], v[192:195], v[0:3]
	v_mfma_f32_16x16x32_bf16 v[52:55], v[204:207], v[172:175], v[52:55]
	v_mfma_f32_16x16x32_bf16 v[44:47], v[212:215], v[172:175], v[44:47]
	v_mfma_f32_16x16x32_bf16 v[36:39], v[204:207], v[180:183], v[36:39]
	v_mfma_f32_16x16x32_bf16 v[28:31], v[212:215], v[180:183], v[28:31]
	v_mfma_f32_16x16x32_bf16 v[20:23], v[204:207], v[188:191], v[20:23]
	v_mfma_f32_16x16x32_bf16 v[12:15], v[212:215], v[188:191], v[12:15]
	v_mfma_f32_16x16x32_bf16 v[4:7], v[204:207], v[196:199], v[4:7]
	v_mfma_f32_16x16x32_bf16 v[0:3], v[212:215], v[196:199], v[0:3]
	s_setprio 0
	s_add_i32 s83, 0, 0x18000
	v_add_u32_e32 v140, s83, v164
	s_barrier
	ds_read_b128 v[128:131], v140
	ds_read_b128 v[132:135], v140 offset:1024
	ds_read_b128 v[136:139], v140 offset:2048
	ds_read_b128 v[140:143], v140 offset:3072
	s_add_u32 s44, s50, 0x40000
	s_addc_u32 s45, s51, 0
	ds_read_b128 v[168:171], v166 offset:32768
	ds_read_b128 v[172:175], v166 offset:33792
	ds_read_b128 v[176:179], v166 offset:34816
	ds_read_b128 v[180:183], v166 offset:35840
	ds_read_b128 v[184:187], v166 offset:36864
	ds_read_b128 v[188:191], v166 offset:37888
	ds_read_b128 v[192:195], v166 offset:38912
	ds_read_b128 v[196:199], v166 offset:39936
	s_mov_b32 m0, s61
	v_lshl_add_u64 v[252:253], s[44:45], 0, v[144:145]
	global_load_lds_dwordx4 v[252:253], off
	v_lshl_add_u64 v[252:253], s[44:45], 0, v[148:149]
	s_mov_b32 m0, s64
	s_nop 0
	global_load_lds_dwordx4 v[252:253], off
	s_add_i32 s50, 0, 0x1c000
	v_add_u32_e32 v152, s50, v164
	ds_read_b128 v[200:203], v152
	ds_read_b128 v[204:207], v152 offset:1024
	ds_read_b128 v[208:211], v152 offset:2048
	ds_read_b128 v[212:215], v152 offset:3072
	s_waitcnt vmcnt(8)
	s_waitcnt lgkmcnt(0)
	s_barrier
	s_setprio 1
	v_mfma_f32_16x16x32_bf16 v[124:127], v[128:131], v[168:171], v[124:127]
	v_mfma_f32_16x16x32_bf16 v[120:123], v[136:139], v[168:171], v[120:123]
	v_mfma_f32_16x16x32_bf16 v[116:119], v[128:131], v[176:179], v[116:119]
	v_mfma_f32_16x16x32_bf16 v[112:115], v[136:139], v[176:179], v[112:115]
	v_mfma_f32_16x16x32_bf16 v[108:111], v[128:131], v[184:187], v[108:111]
	v_mfma_f32_16x16x32_bf16 v[96:99], v[136:139], v[184:187], v[96:99]
	v_mfma_f32_16x16x32_bf16 v[80:83], v[128:131], v[192:195], v[80:83]
	v_mfma_f32_16x16x32_bf16 v[72:75], v[136:139], v[192:195], v[72:75]
	v_mfma_f32_16x16x32_bf16 v[124:127], v[132:135], v[172:175], v[124:127]
	v_mfma_f32_16x16x32_bf16 v[120:123], v[140:143], v[172:175], v[120:123]
	v_mfma_f32_16x16x32_bf16 v[116:119], v[132:135], v[180:183], v[116:119]
	v_mfma_f32_16x16x32_bf16 v[112:115], v[140:143], v[180:183], v[112:115]
	v_mfma_f32_16x16x32_bf16 v[108:111], v[132:135], v[188:191], v[108:111]
	v_mfma_f32_16x16x32_bf16 v[96:99], v[140:143], v[188:191], v[96:99]
	v_mfma_f32_16x16x32_bf16 v[80:83], v[132:135], v[196:199], v[80:83]
	v_mfma_f32_16x16x32_bf16 v[72:75], v[140:143], v[196:199], v[72:75]
	v_mfma_f32_16x16x32_bf16 v[104:107], v[200:203], v[168:171], v[104:107]
	v_mfma_f32_16x16x32_bf16 v[100:103], v[208:211], v[168:171], v[100:103]
	v_mfma_f32_16x16x32_bf16 v[92:95], v[200:203], v[176:179], v[92:95]
	v_mfma_f32_16x16x32_bf16 v[88:91], v[208:211], v[176:179], v[88:91]
	v_mfma_f32_16x16x32_bf16 v[84:87], v[200:203], v[184:187], v[84:87]
	v_mfma_f32_16x16x32_bf16 v[76:79], v[208:211], v[184:187], v[76:79]
	v_mfma_f32_16x16x32_bf16 v[68:71], v[200:203], v[192:195], v[68:71]
	v_mfma_f32_16x16x32_bf16 v[64:67], v[208:211], v[192:195], v[64:67]
	v_mfma_f32_16x16x32_bf16 v[104:107], v[204:207], v[172:175], v[104:107]
	v_mfma_f32_16x16x32_bf16 v[100:103], v[212:215], v[172:175], v[100:103]
	v_mfma_f32_16x16x32_bf16 v[92:95], v[204:207], v[180:183], v[92:95]
	v_mfma_f32_16x16x32_bf16 v[88:91], v[212:215], v[180:183], v[88:91]
	v_mfma_f32_16x16x32_bf16 v[84:87], v[204:207], v[188:191], v[84:87]
	v_mfma_f32_16x16x32_bf16 v[76:79], v[212:215], v[188:191], v[76:79]
	v_mfma_f32_16x16x32_bf16 v[68:71], v[204:207], v[196:199], v[68:71]
	v_mfma_f32_16x16x32_bf16 v[64:67], v[212:215], v[196:199], v[64:67]
	s_setprio 0
	s_barrier
; #define PG8_STAGE(bufoff, gbase, voff) do { _Pragma("unroll") for (int _i = 0; _i < 2; ++_i) \
;         __builtin_amdgcn_global_load_lds((const unsigned*)((const char*)(gbase) + (voff)[_i]), (LAS unsigned*)(lds + (bufoff) + ldsw + _i * 8192), 16, 0, 0); } while (0)
; #define PG8_LDA(dst, b, h) do { _Pragma("unroll") for (int m = 0; m < 4; ++m) _Pragma("unroll") for (int k = 0; k < 2; ++k) dst[m][k] = *(const LAS bf16x8*)(lds + PG8_SA(b, h) + aoff + m * 2048 + k * 1024); } while (0)
; #define PG8_LDB(dst, b, h) do { _Pragma("unroll") for (int n = 0; n < 2; ++n) _Pragma("unroll") for (int k = 0; k < 2; ++k) dst[n][k] = *(const LAS bf16x8*)(lds + PG8_SB(b, h) + boff + n * 2048 + k * 1024); } while (0)
; #define PG8_WAIT_V(n) asm volatile("s_waitcnt vmcnt(" #n ")" ::: "memory")
; #define PG8_WAIT_L(n) asm volatile("s_waitcnt lgkmcnt(" #n ")" ::: "memory")
; #define PG8_BAR __builtin_amdgcn_s_barrier()
; #define PG8_SCHED __builtin_amdgcn_sched_barrier(0)
; template <class Epi>
; __device__ __forceinline__ void gemm_phase(LAS unsigned char* lds, const Gemm g, const StaticOrder& S, const Epi& E, int wv) {
;     ...
;             PG8_LDB(B0, 1, 0); PG8_SCHED; PG8_LDA(At, 1, 0); PG8_STAGE(PG8_SA(0, 1), a2 + hstep, voffA);
;             PG8_WAIT_L(8); PG8_BAR; PG8_WAIT_L(0); PG8_MMA(0, 0, At, B0); PG8_BAR; PG8_SCHED;
;             PG8_LDB(B1, 1, 1); PG8_STAGE(PG8_SB(1, 0), b3, voffB);
;             PG8_BAR; PG8_WAIT_L(0); PG8_MMA(0, 1, At, B1); PG8_BAR;
;             PG8_LDA(At, 1, 1); PG8_STAGE(PG8_SA(1, 0), a3, voffA);
;             PG8_BAR; PG8_WAIT_L(0); PG8_MMA(1, 0, At, B0); PG8_BAR; PG8_SCHED;
;             PG8_STAGE(PG8_SB(1, 1), b3 + hstep, voffB);
;             PG8_WAIT_V(6); PG8_BAR; PG8_MMA(1, 1, At, B1); PG8_BAR;
;     __device__ __forceinline__ void operator()(const f32x4 (&acc)[2][2][4][2], const Unit& u, int wr, int wc, int fr, int fq) const {
;         const float* gate = (u.pm >= 64) ? gate1 : gate0;
;         f32x4 gv[2][2];
; #pragma unroll
;         for (int bj = 0; bj < 2; ++bj)
; #pragma unroll
;             for (int n = 0; n < 2; ++n) gv[bj][n] = *(const f32x4*)(gate + u.pn * 256 + bj * 128 + wc * 32 + n * 16 + 4 * fq);
; #pragma unroll
;         for (int ai = 0; ai < 2; ++ai)
; #pragma unroll
;             for (int m = 0; m < 4; ++m) {
;                 const size_t row = (size_t)u.pm * 256 + ai * 128 + wr * 64 + 4 * fr + m;
	ds_read_b128 v[168:171], v166 offset:49152
	ds_read_b128 v[172:175], v166 offset:50176
	ds_read_b128 v[176:179], v166 offset:51200
	ds_read_b128 v[180:183], v166 offset:52224
	ds_read_b128 v[184:187], v166 offset:53248
	ds_read_b128 v[188:191], v166 offset:54272
	ds_read_b128 v[192:195], v166 offset:55296
	ds_read_b128 v[196:199], v166 offset:56320
	s_add_i32 s44, s83, s58
	v_lshl_add_u64 v[162:163], v[162:163], 0, s[16:17]
	s_mov_b32 m0, s44
	s_nop 0
	global_load_lds_dwordx4 v[162:163], off
	v_lshl_add_u64 v[162:163], v[216:217], 0, s[16:17]
	s_add_i32 m0, s44, 0x2000
	s_nop 0
	global_load_lds_dwordx4 v[162:163], off
	s_mov_b32 m0, s67
	v_lshl_add_u64 v[162:163], v[218:219], 0, s[16:17]
	global_load_lds_dwordx4 v[162:163], off
	v_lshl_add_u64 v[162:163], v[220:221], 0, s[16:17]
	s_mov_b32 m0, s68
	s_nop 0
	global_load_lds_dwordx4 v[162:163], off
	s_add_u32 s44, s48, 0x40080
	s_addc_u32 s45, s49, 0
	s_add_i32 s48, s50, s58
	v_lshl_add_u64 v[254:255], s[44:45], 0, v[146:147]
	s_mov_b32 m0, s48
	s_nop 0
	global_load_lds_dwordx4 v[254:255], off
	v_lshl_add_u64 v[254:255], s[44:45], 0, v[150:151]
	s_add_i32 m0, s48, 0x2000
	s_nop 0
	global_load_lds_dwordx4 v[254:255], off
	s_waitcnt vmcnt(8)
	s_waitcnt lgkmcnt(0)
	s_barrier
	s_setprio 1
	v_mfma_f32_16x16x32_bf16 v[60:63], v[128:131], v[168:171], v[60:63]
	v_mfma_f32_16x16x32_bf16 v[56:59], v[136:139], v[168:171], v[56:59]
	v_mfma_f32_16x16x32_bf16 v[48:51], v[128:131], v[176:179], v[48:51]
	v_mfma_f32_16x16x32_bf16 v[40:43], v[136:139], v[176:179], v[40:43]
	v_mfma_f32_16x16x32_bf16 v[32:35], v[128:131], v[184:187], v[32:35]
	v_mfma_f32_16x16x32_bf16 v[24:27], v[136:139], v[184:187], v[24:27]
	v_mfma_f32_16x16x32_bf16 v[16:19], v[128:131], v[192:195], v[16:19]
	v_mfma_f32_16x16x32_bf16 v[8:11], v[136:139], v[192:195], v[8:11]
	v_mfma_f32_16x16x32_bf16 v[60:63], v[132:135], v[172:175], v[60:63]
	v_mfma_f32_16x16x32_bf16 v[56:59], v[140:143], v[172:175], v[56:59]
	v_mfma_f32_16x16x32_bf16 v[48:51], v[132:135], v[180:183], v[48:51]
	v_mfma_f32_16x16x32_bf16 v[40:43], v[140:143], v[180:183], v[40:43]
	v_mfma_f32_16x16x32_bf16 v[32:35], v[132:135], v[188:191], v[32:35]
	v_mfma_f32_16x16x32_bf16 v[24:27], v[140:143], v[188:191], v[24:27]
	v_mfma_f32_16x16x32_bf16 v[16:19], v[132:135], v[196:199], v[16:19]
	v_mfma_f32_16x16x32_bf16 v[8:11], v[140:143], v[196:199], v[8:11]
	v_mfma_f32_16x16x32_bf16 v[52:55], v[200:203], v[168:171], v[52:55]
	v_mfma_f32_16x16x32_bf16 v[44:47], v[208:211], v[168:171], v[44:47]
	v_mfma_f32_16x16x32_bf16 v[36:39], v[200:203], v[176:179], v[36:39]
	v_mfma_f32_16x16x32_bf16 v[28:31], v[208:211], v[176:179], v[28:31]
	v_mfma_f32_16x16x32_bf16 v[20:23], v[200:203], v[184:187], v[20:23]
	v_mfma_f32_16x16x32_bf16 v[12:15], v[208:211], v[184:187], v[12:15]
	v_mfma_f32_16x16x32_bf16 v[4:7], v[200:203], v[192:195], v[4:7]
	v_mfma_f32_16x16x32_bf16 v[0:3], v[208:211], v[192:195], v[0:3]
	v_mfma_f32_16x16x32_bf16 v[52:55], v[204:207], v[172:175], v[52:55]
	v_mfma_f32_16x16x32_bf16 v[44:47], v[212:215], v[172:175], v[44:47]
	v_mfma_f32_16x16x32_bf16 v[36:39], v[204:207], v[180:183], v[36:39]
	v_mfma_f32_16x16x32_bf16 v[28:31], v[212:215], v[180:183], v[28:31]
	v_mfma_f32_16x16x32_bf16 v[20:23], v[204:207], v[188:191], v[20:23]
	v_mfma_f32_16x16x32_bf16 v[12:15], v[212:215], v[188:191], v[12:15]
	v_mfma_f32_16x16x32_bf16 v[4:7], v[204:207], v[196:199], v[4:7]
	v_mfma_f32_16x16x32_bf16 v[0:3], v[212:215], v[196:199], v[0:3]
	s_setprio 0
	s_add_i32 s82, s82, 2
	s_add_u32 s80, s80, 0x100
	s_addc_u32 s81, s81, 0
	s_cmp_gt_u32 s82, 13
	s_mov_b64 s[44:45], s[46:47]
	s_barrier
	s_cbranch_scc0 .LBB0_846
	s_mov_b32 s35, -1
	s_cmp_gt_i32 s42, 63
	v_mbcnt_lo_u32_b32 v128, s35, 0
	v_mbcnt_hi_u32_b32 v152, s35, v128
	s_cselect_b32 s35, s74, 0x1642000
	s_add_u32 s35, s6, s35
	s_addc_u32 s37, s7, 0
	s_lshl_b32 s44, s8, 8
	s_ashr_i32 s45, s44, 31
	s_lshl_b64 s[46:47], s[44:45], 2
	s_add_u32 s8, s35, s46
	s_addc_u32 s35, s37, s47
	s_lshl_b32 s37, s66, 2
	v_lshrrev_b32_e32 v128, 2, v152
	s_add_u32 s46, s8, s37
	v_and_b32_e32 v162, 28, v128
	s_addc_u32 s47, s35, 0
	v_lshlrev_b32_e32 v128, 2, v162
	global_load_dwordx4 v[140:143], v128, s[46:47]
	global_load_dwordx4 v[136:139], v128, s[46:47] offset:64
	global_load_dwordx4 v[132:135], v128, s[46:47] offset:512
	s_nop 0
	global_load_dwordx4 v[128:131], v128, s[46:47] offset:576
	s_ashr_i32 s43, s42, 31
	s_lshl_b64 s[42:43], s[42:43], 8
	s_add_u32 s8, s42, s65
	v_lshlrev_b32_e32 v163, 2, v152
	s_addc_u32 s35, s43, s69
	v_bfe_u32 v222, v152, 5, 1
	v_bfe_u32 v152, v152, 4, 1
	v_lshlrev_b32_e32 v222, 4, v222
	v_lshl_or_b32 v152, v152, 5, v222
	v_and_or_b32 v162, v163, 60, s8
	v_mov_b32_e32 v163, s35
	v_lshlrev_b64 v[162:163], 11, v[162:163]
	v_lshl_add_u64 v[162:163], s[14:15], 0, v[162:163]
	s_lshl_b32 s8, s66, 1
	v_lshl_add_u64 v[162:163], s[44:45], 1, v[162:163]
	v_lshl_add_u64 v[162:163], v[162:163], 0, s[8:9]
	v_lshl_add_u64 v[162:163], v[162:163], 0, v[152:153]
	v_lshl_add_u64 v[168:169], v[162:163], 0, s[18:19]
	v_lshl_add_u64 v[170:171], v[162:163], 0, s[12:13]
	s_mov_b32 s8, s34
	s_nop 0
	v_lshl_add_u64 v[222:223], v[162:163], 0, s[28:29]
	s_mov_b32 s42, s36
	s_mov_b64 s[46:47], s[40:41]
	s_mov_b64 s[44:45], s[38:39]
	s_waitcnt vmcnt(0)
; __device__ __forceinline__ unsigned pk2(float lo, float hi) { unsigned r; asm("v_cvt_pk_bf16_f32 %0, %1, %2" : "=v"(r) : "v"(lo), "v"(hi)); return r; }
;     __device__ __forceinline__ void operator()(const f32x4 (&acc)[2][2][4][2], const Unit& u, int wr, int wc, int fr, int fq) const {
;     ...
;                 for (int bj = 0; bj < 2; ++bj)
; #pragma unroll
;                     for (int n = 0; n < 2; ++n) {
;                         const f32x4 v = gv[bj][n] * acc[ai][bj][m][n];
;                         u32x2 w; w.x = pk2(v[0], v[1]); w.y = pk2(v[2], v[3]);
;                         *(u32x2*)(O + row * D + u.pn * 256 + bj * 128 + wc * 32 + n * 16 + 4 * fq) = w;
;                     }
;             }
	v_pk_mul_f32 v[124:125], v[124:125], v[140:141]
	v_pk_mul_f32 v[126:127], v[126:127], v[142:143]
	v_pk_mul_f32 v[120:121], v[120:121], v[136:137]
	v_pk_mul_f32 v[122:123], v[122:123], v[138:139]
	v_cvt_pk_bf16_f32 v124, v124, v125
	v_cvt_pk_bf16_f32 v125, v126, v127
	v_cvt_pk_bf16_f32 v126, v120, v121
	v_cvt_pk_bf16_f32 v127, v122, v123
	v_pk_mul_f32 v[104:105], v[104:105], v[132:133]
	v_pk_mul_f32 v[106:107], v[106:107], v[134:135]
	v_pk_mul_f32 v[100:101], v[100:101], v[128:129]
	v_pk_mul_f32 v[102:103], v[102:103], v[130:131]
	v_permlane16_swap_b32_e32 v124, v126
	v_permlane16_swap_b32_e32 v125, v127
	global_store_dwordx4 v[162:163], v[124:127], off
	v_cvt_pk_bf16_f32 v104, v104, v105
	v_cvt_pk_bf16_f32 v105, v106, v107
	v_cvt_pk_bf16_f32 v106, v100, v101
	v_cvt_pk_bf16_f32 v107, v102, v103
	v_pk_mul_f32 v[116:117], v[116:117], v[140:141]
	v_pk_mul_f32 v[118:119], v[118:119], v[142:143]
	v_pk_mul_f32 v[112:113], v[112:113], v[136:137]
	v_pk_mul_f32 v[114:115], v[114:115], v[138:139]
	v_permlane16_swap_b32_e32 v104, v106
	v_permlane16_swap_b32_e32 v105, v107
	global_store_dwordx4 v[162:163], v[104:107], off offset:256
	v_cvt_pk_bf16_f32 v116, v116, v117
	v_cvt_pk_bf16_f32 v117, v118, v119
	v_cvt_pk_bf16_f32 v118, v112, v113
	v_cvt_pk_bf16_f32 v119, v114, v115
	v_pk_mul_f32 v[92:93], v[92:93], v[132:133]
	v_pk_mul_f32 v[94:95], v[94:95], v[134:135]
	v_pk_mul_f32 v[88:89], v[88:89], v[128:129]
	v_pk_mul_f32 v[90:91], v[90:91], v[130:131]
	v_permlane16_swap_b32_e32 v116, v118
	v_permlane16_swap_b32_e32 v117, v119
	global_store_dwordx4 v[162:163], v[116:119], off offset:2048
	v_cvt_pk_bf16_f32 v92, v92, v93
	v_cvt_pk_bf16_f32 v93, v94, v95
	v_cvt_pk_bf16_f32 v94, v88, v89
	v_cvt_pk_bf16_f32 v95, v90, v91
	v_pk_mul_f32 v[108:109], v[108:109], v[140:141]
	v_pk_mul_f32 v[110:111], v[110:111], v[142:143]
	v_pk_mul_f32 v[96:97], v[96:97], v[136:137]
	v_pk_mul_f32 v[98:99], v[98:99], v[138:139]
	v_permlane16_swap_b32_e32 v92, v94
	v_permlane16_swap_b32_e32 v93, v95
	global_store_dwordx4 v[162:163], v[92:95], off offset:2304
	v_cvt_pk_bf16_f32 v108, v108, v109
	v_cvt_pk_bf16_f32 v109, v110, v111
	v_cvt_pk_bf16_f32 v110, v96, v97
	v_cvt_pk_bf16_f32 v111, v98, v99
	v_pk_mul_f32 v[84:85], v[84:85], v[132:133]
	v_pk_mul_f32 v[86:87], v[86:87], v[134:135]
	v_pk_mul_f32 v[76:77], v[76:77], v[128:129]
	v_pk_mul_f32 v[78:79], v[78:79], v[130:131]
	v_permlane16_swap_b32_e32 v108, v110
	v_permlane16_swap_b32_e32 v109, v111
	global_store_dwordx4 v[168:169], v[108:111], off
	v_cvt_pk_bf16_f32 v84, v84, v85
	v_cvt_pk_bf16_f32 v85, v86, v87
	v_cvt_pk_bf16_f32 v86, v76, v77
	v_cvt_pk_bf16_f32 v87, v78, v79
	v_pk_mul_f32 v[80:81], v[80:81], v[140:141]
	v_pk_mul_f32 v[82:83], v[82:83], v[142:143]
	v_pk_mul_f32 v[72:73], v[72:73], v[136:137]
	v_pk_mul_f32 v[74:75], v[74:75], v[138:139]
	v_permlane16_swap_b32_e32 v84, v86
	v_permlane16_swap_b32_e32 v85, v87
	global_store_dwordx4 v[168:169], v[84:87], off offset:256
	v_cvt_pk_bf16_f32 v80, v80, v81
	v_cvt_pk_bf16_f32 v81, v82, v83
	v_cvt_pk_bf16_f32 v82, v72, v73
	v_cvt_pk_bf16_f32 v83, v74, v75
	v_pk_mul_f32 v[68:69], v[68:69], v[132:133]
	v_pk_mul_f32 v[70:71], v[70:71], v[134:135]
	v_pk_mul_f32 v[64:65], v[64:65], v[128:129]
	v_pk_mul_f32 v[66:67], v[66:67], v[130:131]
	v_permlane16_swap_b32_e32 v80, v82
	v_permlane16_swap_b32_e32 v81, v83
	global_store_dwordx4 v[168:169], v[80:83], off offset:2048
	v_cvt_pk_bf16_f32 v68, v68, v69
	v_cvt_pk_bf16_f32 v69, v70, v71
	v_cvt_pk_bf16_f32 v70, v64, v65
	v_cvt_pk_bf16_f32 v71, v66, v67
	v_pk_mul_f32 v[60:61], v[60:61], v[140:141]
	v_pk_mul_f32 v[62:63], v[62:63], v[142:143]
	v_pk_mul_f32 v[56:57], v[56:57], v[136:137]
; __device__ __forceinline__ int lane_fresh() { unsigned m = ~0u; asm volatile("" : "+s"(m)); return (int)__builtin_amdgcn_mbcnt_hi(m, __builtin_amdgcn_mbcnt_lo(m, 0u)); }
; __device__ __forceinline__ unsigned pk2(float lo, float hi) { unsigned r; asm("v_cvt_pk_bf16_f32 %0, %1, %2" : "=v"(r) : "v"(lo), "v"(hi)); return r; }
; #define PG8_WAIT_V(n) asm volatile("s_waitcnt vmcnt(" #n ")" ::: "memory")
; #define PG8_BAR __builtin_amdgcn_s_barrier()
; template <class Epi>
; __device__ __forceinline__ void gemm_phase(LAS unsigned char* lds, const Gemm g, const StaticOrder& S, const Epi& E, int wv) {
;     ...
;         { const int ln2 = lane_fresh();
;           E(acc, cur, wr, wc, ln2 & 15, ln2 >> 4); }
;         if (!has_next) break;
; #pragma unroll
;         for (int a = 0; a < 2; ++a)
; #pragma unroll
;             for (int b = 0; b < 2; ++b)
; #pragma unroll
;                 for (int m = 0; m < 4; ++m)
; #pragma unroll
;                     for (int n = 0; n < 2; ++n) acc[a][b][m][n] = (f32x4){0.f, 0.f, 0.f, 0.f};
;         cur = nxt; cA = nA; cB = nB; ++ui;
;     }
;     PG8_WAIT_V(0);
;     if (wr == 0) PG8_BAR;
;     PG8_BAR;
;     __device__ __forceinline__ void operator()(const f32x4 (&acc)[2][2][4][2], const Unit& u, int wr, int wc, int fr, int fq) const {
;     ...
;                 for (int bj = 0; bj < 2; ++bj)
; #pragma unroll
;                     for (int n = 0; n < 2; ++n) {
;                         const f32x4 v = gv[bj][n] * acc[ai][bj][m][n];
;                         u32x2 w; w.x = pk2(v[0], v[1]); w.y = pk2(v[2], v[3]);
;                         *(u32x2*)(O + row * D + u.pn * 256 + bj * 128 + wc * 32 + n * 16 + 4 * fq) = w;
;                     }
;             }
	v_pk_mul_f32 v[58:59], v[58:59], v[138:139]
	v_permlane16_swap_b32_e32 v68, v70
	v_permlane16_swap_b32_e32 v69, v71
	global_store_dwordx4 v[168:169], v[68:71], off offset:2304
	v_cvt_pk_bf16_f32 v60, v60, v61
	v_cvt_pk_bf16_f32 v61, v62, v63
	v_cvt_pk_bf16_f32 v62, v56, v57
	v_cvt_pk_bf16_f32 v63, v58, v59
	v_pk_mul_f32 v[52:53], v[52:53], v[132:133]
	v_pk_mul_f32 v[54:55], v[54:55], v[134:135]
	v_pk_mul_f32 v[44:45], v[44:45], v[128:129]
	v_pk_mul_f32 v[46:47], v[46:47], v[130:131]
	v_permlane16_swap_b32_e32 v60, v62
	v_permlane16_swap_b32_e32 v61, v63
	global_store_dwordx4 v[170:171], v[60:63], off
	v_cvt_pk_bf16_f32 v52, v52, v53
	v_cvt_pk_bf16_f32 v53, v54, v55
	v_cvt_pk_bf16_f32 v54, v44, v45
	v_cvt_pk_bf16_f32 v55, v46, v47
	v_pk_mul_f32 v[48:49], v[48:49], v[140:141]
	v_pk_mul_f32 v[50:51], v[50:51], v[142:143]
	v_pk_mul_f32 v[40:41], v[40:41], v[136:137]
	v_pk_mul_f32 v[42:43], v[42:43], v[138:139]
	v_permlane16_swap_b32_e32 v52, v54
	v_permlane16_swap_b32_e32 v53, v55
	global_store_dwordx4 v[170:171], v[52:55], off offset:256
	v_cvt_pk_bf16_f32 v48, v48, v49
	v_cvt_pk_bf16_f32 v49, v50, v51
	v_cvt_pk_bf16_f32 v50, v40, v41
	v_cvt_pk_bf16_f32 v51, v42, v43
	v_pk_mul_f32 v[36:37], v[36:37], v[132:133]
	v_pk_mul_f32 v[38:39], v[38:39], v[134:135]
	v_pk_mul_f32 v[28:29], v[28:29], v[128:129]
	v_pk_mul_f32 v[30:31], v[30:31], v[130:131]
	v_permlane16_swap_b32_e32 v48, v50
	v_permlane16_swap_b32_e32 v49, v51
	global_store_dwordx4 v[170:171], v[48:51], off offset:2048
	v_cvt_pk_bf16_f32 v36, v36, v37
	v_cvt_pk_bf16_f32 v37, v38, v39
	v_cvt_pk_bf16_f32 v38, v28, v29
	v_cvt_pk_bf16_f32 v39, v30, v31
	v_pk_mul_f32 v[32:33], v[32:33], v[140:141]
	v_pk_mul_f32 v[34:35], v[34:35], v[142:143]
	v_pk_mul_f32 v[24:25], v[24:25], v[136:137]
	v_pk_mul_f32 v[26:27], v[26:27], v[138:139]
	v_permlane16_swap_b32_e32 v36, v38
	v_permlane16_swap_b32_e32 v37, v39
	global_store_dwordx4 v[170:171], v[36:39], off offset:2304
	v_cvt_pk_bf16_f32 v32, v32, v33
	v_cvt_pk_bf16_f32 v33, v34, v35
	v_cvt_pk_bf16_f32 v34, v24, v25
	v_cvt_pk_bf16_f32 v35, v26, v27
	v_pk_mul_f32 v[20:21], v[20:21], v[132:133]
	v_pk_mul_f32 v[22:23], v[22:23], v[134:135]
	v_pk_mul_f32 v[12:13], v[12:13], v[128:129]
	v_pk_mul_f32 v[14:15], v[14:15], v[130:131]
	v_permlane16_swap_b32_e32 v32, v34
	v_permlane16_swap_b32_e32 v33, v35
	global_store_dwordx4 v[222:223], v[32:35], off
	v_cvt_pk_bf16_f32 v20, v20, v21
	v_cvt_pk_bf16_f32 v21, v22, v23
	v_cvt_pk_bf16_f32 v22, v12, v13
	v_cvt_pk_bf16_f32 v23, v14, v15
	v_pk_mul_f32 v[16:17], v[16:17], v[140:141]
	v_pk_mul_f32 v[18:19], v[18:19], v[142:143]
	v_pk_mul_f32 v[8:9], v[8:9], v[136:137]
	v_pk_mul_f32 v[10:11], v[10:11], v[138:139]
	v_permlane16_swap_b32_e32 v20, v22
	v_permlane16_swap_b32_e32 v21, v23
	global_store_dwordx4 v[222:223], v[20:23], off offset:256
	v_cvt_pk_bf16_f32 v16, v16, v17
	v_cvt_pk_bf16_f32 v17, v18, v19
	v_cvt_pk_bf16_f32 v18, v8, v9
	v_cvt_pk_bf16_f32 v19, v10, v11
	v_pk_mul_f32 v[4:5], v[4:5], v[132:133]
	v_pk_mul_f32 v[6:7], v[6:7], v[134:135]
	v_pk_mul_f32 v[0:1], v[0:1], v[128:129]
	v_pk_mul_f32 v[2:3], v[2:3], v[130:131]
	v_permlane16_swap_b32_e32 v16, v18
	v_permlane16_swap_b32_e32 v17, v19
	global_store_dwordx4 v[222:223], v[16:19], off offset:2048
	v_cvt_pk_bf16_f32 v4, v4, v5
	v_cvt_pk_bf16_f32 v5, v6, v7
	v_cvt_pk_bf16_f32 v6, v0, v1
	v_cvt_pk_bf16_f32 v7, v2, v3
	s_nop 1
	v_permlane16_swap_b32_e32 v4, v6
	v_permlane16_swap_b32_e32 v5, v7
	global_store_dwordx4 v[222:223], v[4:7], off offset:2304
	s_and_b64 vcc, exec, s[4:5]
	s_cbranch_vccz .LBB0_839
	s_waitcnt vmcnt(0)
	s_cmpk_gt_u32 s52, 0xff
	s_cbranch_scc1 .LBB0_850
	s_barrier

; #define PG8_STAGE(bufoff, gbase, voff) do { _Pragma("unroll") for (int _i = 0; _i < 2; ++_i) \
;         __builtin_amdgcn_global_load_lds((const unsigned*)((const char*)(gbase) + (voff)[_i]), (LAS unsigned*)(lds + (bufoff) + ldsw + _i * 8192), 16, 0, 0); } while (0)
; #define PG8_WAIT_V(n) asm volatile("s_waitcnt vmcnt(" #n ")" ::: "memory")
; #define PG8_BAR __builtin_amdgcn_s_barrier()
; template <class Epi>
; __device__ __forceinline__ void gemm_phase(LAS unsigned char* lds, const Gemm g, const StaticOrder& S, const Epi& E, int wv) {
;     ...
;     const int wid = __builtin_amdgcn_readfirstlane(tid >> 6), lane = tid & 63, wr = wid >> 2, wc = wid & 3, fr = lane & 15, fq = lane >> 4;
;     const int K = g.K, nt = K / BK;
;     unsigned voffA[2], voffB[2];
; #pragma unroll
;     for (int i = 0; i < 2; ++i) { int R, C; stage_rc(tid * 16 + i * 8192, R, C);
;         const int Ra = (R & ~63) + 4 * (R & 15) + ((R >> 4) & 3);
;         voffA[i] = (unsigned)(Ra * K + C) * 2u; voffB[i] = (unsigned)(R * K + C) * 2u; }
;     const size_t kstep = (size_t)(BK * 2);
;     const size_t hstep = (size_t)HALF * K * 2;
;     const size_t tstepA = (size_t)g.a_tile_rows * K * 2;
;     const size_t tstepB = 2 * hstep;
;     const unsigned ldsw = (unsigned)wid * 1024u;
;     const int aoff = lds_byte(wr * 64 + fr, fq * 8), boff = lds_byte(wc * 32 + fr, fq * 8);
;     ...
;     const char* cA = (const char*)g.A + (size_t)cur.pm * tstepA; const char* cB = (const char*)g.Bt + (size_t)cur.pn * tstepB;
;     PG8_STAGE(PG8_SB(0, 0), cB, voffB); PG8_STAGE(PG8_SA(0, 0), cA, voffA); PG8_STAGE(PG8_SB(0, 1), cB + hstep, voffB); PG8_STAGE(PG8_SA(0, 1), cA + hstep, voffA);
;     if (wr == 1) PG8_BAR;
;     PG8_WAIT_V(4); PG8_BAR;
;     PG8_STAGE(PG8_SB(1, 0), cB + kstep, voffB); PG8_STAGE(PG8_SA(1, 0), cA + kstep, voffA); PG8_STAGE(PG8_SB(1, 1), cB + hstep + kstep, voffB);
;     PG8_WAIT_V(6); PG8_BAR;
.LBB0_988:
	s_add_u32 s28, s4, 0x1c77000
	s_mov_b64 s[30:31], 0x80
	s_addc_u32 s29, s5, 0
	s_and_b32 s6, s6, 3
	s_add_i32 m0, s68, 0x18000
	v_lshl_add_u64 v[6:7], v[6:7], 0, s[30:31]
	s_lshl_b32 s75, s7, 6
	s_lshl_b32 s9, s7, 13
	s_lshl_b32 s76, s6, 5
	s_lshl_b32 s17, s6, 12
	s_waitcnt vmcnt(2)
	s_barrier
	global_load_lds_dwordx4 v[6:7], off
	v_lshl_add_u64 v[4:5], v[4:5], 0, s[30:31]
	s_add_i32 m0, s68, 0x1a000
	s_add_i32 s77, s68, 0x8000
	s_add_i32 s78, s68, 0xa000
	global_load_lds_dwordx4 v[4:5], off
	v_lshl_add_u64 v[2:3], v[2:3], 0, s[30:31]
	s_mov_b32 m0, s77
	s_add_u32 s4, s14, 0x40080
	global_load_lds_dwordx4 v[2:3], off
	v_lshl_add_u64 v[0:1], v[0:1], 0, s[30:31]
	s_mov_b32 m0, s78
	s_addc_u32 s5, s15, 0
	global_load_lds_dwordx4 v[0:1], off
	s_add_i32 m0, s68, 0x1c000
	v_lshl_add_u64 v[0:1], s[4:5], 0, v[162:163]
	global_load_lds_dwordx4 v[0:1], off
	v_lshl_add_u64 v[0:1], s[4:5], 0, v[166:167]
	s_add_i32 m0, s68, 0x1e000
	s_cmpk_lt_u32 s16, 0x100
	global_load_lds_dwordx4 v[0:1], off
	v_and_b32_e32 v0, 15, v8
	v_and_b32_e32 v1, 48, v8
	v_lshl_or_b32 v0, v0, 6, v1
	v_lshlrev_b32_e32 v1, 2, v8
	s_cselect_b64 s[34:35], -1, 0
	s_lshl_b32 s6, s6, 7
	s_lshl_b32 s79, s7, 11
	v_and_b32_e32 v1, 32, v1
	s_add_i32 s80, s6, 0
	s_add_i32 s6, s79, 0x1800
	v_bitop3_b32 v2, v0, s9, v1 bitop3:0xde
	v_bitop3_b32 v213, v0, s17, v1 bitop3:0xde
	s_add_i32 s80, s80, 0x20000
	s_and_b32 s82, s6, 0x1800
	s_add_i32 s6, s79, 0x800
	v_and_b32_e32 v1, 1, v9
	s_add_i32 s81, s79, s80
	s_and_b32 s83, s6, 0x1800
	s_ashr_i32 s84, s24, 31
	s_ashr_i32 s86, s2, 31
	v_add3_u32 v0, v11, v12, v13
	v_lshlrev_b32_e32 v1, 6, v1
	s_add_u32 s36, s20, 0x5800
	v_lshl_or_b32 v0, v0, 11, v1
	v_and_b32_e32 v1, 1, v14
	s_addc_u32 s37, s21, 0
	v_lshl_add_u32 v168, v10, 1, v0
	v_add3_u32 v0, v16, v17, v18
	v_lshlrev_b32_e32 v1, 6, v1
	s_mov_b64 s[4:5], 0x40080
	s_waitcnt vmcnt(6)
	s_add_u32 s38, s20, 0xb000
	v_lshl_or_b32 v0, v0, 11, v1
	s_addc_u32 s39, s21, 0
	v_lshl_add_u64 v[170:171], v[168:169], 0, s[4:5]
	v_lshl_add_u32 v168, v15, 1, v0
	s_add_i32 s90, 0, 0x10000
	s_add_i32 s91, 0, 0x14000
	s_mov_b32 s85, s24
	s_add_i32 s87, s81, 0x1000
	s_add_i32 s88, s80, s82
	s_add_i32 s89, s80, s83
	v_lshl_add_u64 v[172:173], v[168:169], 0, s[4:5]
	v_mov_b64_e32 v[174:175], 0xb2c
	v_mov_b64_e32 v[176:177], 0xb2b
	v_add_u32_e32 v214, s90, v213
	v_add_u32_e32 v215, 0, v2
	v_add_u32_e32 v216, s91, v213
	s_movk_i32 s92, 0xfe
	s_movk_i32 s93, 0x407e
	s_movk_i32 s94, 0x1600
	s_movk_i32 s95, 0xff
	v_mov_b32_e32 v217, 0xffffbf82
	v_mov_b32_e32 v218, 0x4000
	s_barrier
	s_branch .LBB0_990

; #define PG8_STAGE(bufoff, gbase, voff) do { _Pragma("unroll") for (int _i = 0; _i < 2; ++_i) \
;         __builtin_amdgcn_global_load_lds((const unsigned*)((const char*)(gbase) + (voff)[_i]), (LAS unsigned*)(lds + (bufoff) + ldsw + _i * 8192), 16, 0, 0); } while (0)
; #define PG8_LDA(dst, b, h) do { _Pragma("unroll") for (int m = 0; m < 4; ++m) _Pragma("unroll") for (int k = 0; k < 2; ++k) dst[m][k] = *(const LAS bf16x8*)(lds + PG8_SA(b, h) + aoff + m * 2048 + k * 1024); } while (0)
; #define PG8_LDB(dst, b, h) do { _Pragma("unroll") for (int n = 0; n < 2; ++n) _Pragma("unroll") for (int k = 0; k < 2; ++k) dst[n][k] = *(const LAS bf16x8*)(lds + PG8_SB(b, h) + boff + n * 2048 + k * 1024); } while (0)
; #define PG8_MMA(ai, bj, At, Bt) do { __builtin_amdgcn_s_setprio(1); _Pragma("unroll") for (int m = 0; m < 4; ++m) _Pragma("unroll") for (int n = 0; n < 2; ++n) _Pragma("unroll") for (int k = 0; k < 2; ++k) \
;         acc[ai][bj][m][n] = __builtin_amdgcn_mfma_f32_16x16x32_bf16(Bt[n][k], At[m][k], acc[ai][bj][m][n], 0, 0, 0); __builtin_amdgcn_s_setprio(0); } while (0)
; #define PG8_WAIT_V(n) asm volatile("s_waitcnt vmcnt(" #n ")" ::: "memory")
; #define PG8_WAIT_L(n) asm volatile("s_waitcnt lgkmcnt(" #n ")" ::: "memory")
; #define PG8_BAR __builtin_amdgcn_s_barrier()
; #define PG8_SCHED __builtin_amdgcn_sched_barrier(0)
; template <class Epi>
; __device__ __forceinline__ void gemm_phase(LAS unsigned char* lds, const Gemm g, const StaticOrder& S, const Epi& E, int wv) {
;     ...
;             PG8_LDB(B0, 0, 0); PG8_SCHED; PG8_LDA(At, 0, 0); PG8_STAGE(PG8_SA(1, 1), a1 + hstep, voffA);
;             PG8_WAIT_L(8); PG8_BAR; PG8_WAIT_L(0); PG8_MMA(0, 0, At, B0); PG8_BAR; PG8_SCHED;
;             PG8_LDB(B1, 0, 1); PG8_STAGE(PG8_SB(0, 0), b2, voffB);
;             PG8_BAR; PG8_WAIT_L(0); PG8_MMA(0, 1, At, B1); PG8_BAR;
;             PG8_LDA(At, 0, 1); PG8_STAGE(PG8_SA(0, 0), a2, voffA);
;             PG8_BAR; PG8_WAIT_L(0); PG8_MMA(1, 0, At, B0); PG8_BAR; PG8_SCHED;
;             PG8_STAGE(PG8_SB(0, 1), b2 + hstep, voffB);
;             PG8_WAIT_V(6); PG8_BAR; PG8_MMA(1, 1, At, B1); PG8_BAR;
.LBB0_999:
	ds_read_b128 v[128:131], v214
	ds_read_b128 v[132:135], v214 offset:1024
	ds_read_b128 v[136:139], v214 offset:2048
	ds_read_b128 v[140:143], v214 offset:3072
	s_add_u32 s6, s12, 0x100
	s_addc_u32 s7, s13, 0
	s_cmp_eq_u32 s49, 12
	s_cselect_b32 s17, s43, s7
	s_cselect_b32 s16, s42, s6
	s_cselect_b32 s15, s9, s48
	s_cselect_b32 s14, s41, s46
	ds_read_b128 v[144:147], v215
	ds_read_b128 v[148:151], v215 offset:1024
	ds_read_b128 v[152:155], v215 offset:2048
	ds_read_b128 v[156:159], v215 offset:3072
	ds_read_b128 v[178:181], v215 offset:4096
	ds_read_b128 v[182:185], v215 offset:5120
	ds_read_b128 v[186:189], v215 offset:6144
	ds_read_b128 v[190:193], v215 offset:7168
	ds_read_b128 v[194:197], v216
	ds_read_b128 v[198:201], v216 offset:1024
	ds_read_b128 v[202:205], v216 offset:2048
	ds_read_b128 v[206:209], v216 offset:3072
	v_lshl_add_u64 v[252:253], s[12:13], 0, v[170:171]
	s_add_i32 m0, s68, 0xc000
	s_nop 0
	global_load_lds_dwordx4 v[252:253], off
	v_lshl_add_u64 v[252:253], s[12:13], 0, v[172:173]
	s_add_i32 m0, s68, 0xe000
	s_nop 0
	global_load_lds_dwordx4 v[252:253], off
	s_waitcnt vmcnt(8)
	s_waitcnt lgkmcnt(0)
	s_barrier
	s_setprio 1
	v_mfma_f32_16x16x32_bf16 v[124:127], v[128:131], v[144:147], v[124:127]
	v_mfma_f32_16x16x32_bf16 v[60:63], v[136:139], v[144:147], v[60:63]
	v_mfma_f32_16x16x32_bf16 v[116:119], v[128:131], v[152:155], v[116:119]
	v_mfma_f32_16x16x32_bf16 v[52:55], v[136:139], v[152:155], v[52:55]
	v_mfma_f32_16x16x32_bf16 v[112:115], v[128:131], v[178:181], v[112:115]
	v_mfma_f32_16x16x32_bf16 v[48:51], v[136:139], v[178:181], v[48:51]
	v_mfma_f32_16x16x32_bf16 v[108:111], v[128:131], v[186:189], v[108:111]
	v_mfma_f32_16x16x32_bf16 v[44:47], v[136:139], v[186:189], v[44:47]
	v_mfma_f32_16x16x32_bf16 v[124:127], v[132:135], v[148:151], v[124:127]
	v_mfma_f32_16x16x32_bf16 v[60:63], v[140:143], v[148:151], v[60:63]
	v_mfma_f32_16x16x32_bf16 v[116:119], v[132:135], v[156:159], v[116:119]
	v_mfma_f32_16x16x32_bf16 v[52:55], v[140:143], v[156:159], v[52:55]
	v_mfma_f32_16x16x32_bf16 v[112:115], v[132:135], v[182:185], v[112:115]
	v_mfma_f32_16x16x32_bf16 v[48:51], v[140:143], v[182:185], v[48:51]
	v_mfma_f32_16x16x32_bf16 v[108:111], v[132:135], v[190:193], v[108:111]
	v_mfma_f32_16x16x32_bf16 v[44:47], v[140:143], v[190:193], v[44:47]
	v_mfma_f32_16x16x32_bf16 v[120:123], v[194:197], v[144:147], v[120:123]
	v_mfma_f32_16x16x32_bf16 v[56:59], v[202:205], v[144:147], v[56:59]
	v_mfma_f32_16x16x32_bf16 v[104:107], v[194:197], v[152:155], v[104:107]
	v_mfma_f32_16x16x32_bf16 v[40:43], v[202:205], v[152:155], v[40:43]
	v_mfma_f32_16x16x32_bf16 v[100:103], v[194:197], v[178:181], v[100:103]
	v_mfma_f32_16x16x32_bf16 v[36:39], v[202:205], v[178:181], v[36:39]
	v_mfma_f32_16x16x32_bf16 v[96:99], v[194:197], v[186:189], v[96:99]
	v_mfma_f32_16x16x32_bf16 v[32:35], v[202:205], v[186:189], v[32:35]
	v_mfma_f32_16x16x32_bf16 v[120:123], v[198:201], v[148:151], v[120:123]
	v_mfma_f32_16x16x32_bf16 v[56:59], v[206:209], v[148:151], v[56:59]
	v_mfma_f32_16x16x32_bf16 v[104:107], v[198:201], v[156:159], v[104:107]
	v_mfma_f32_16x16x32_bf16 v[40:43], v[206:209], v[156:159], v[40:43]
	v_mfma_f32_16x16x32_bf16 v[100:103], v[198:201], v[182:185], v[100:103]
	v_mfma_f32_16x16x32_bf16 v[36:39], v[206:209], v[182:185], v[36:39]
	v_mfma_f32_16x16x32_bf16 v[96:99], v[198:201], v[190:193], v[96:99]
	v_mfma_f32_16x16x32_bf16 v[32:35], v[206:209], v[190:193], v[32:35]
	s_setprio 0
	s_barrier
	ds_read_b128 v[144:147], v215 offset:16384
	ds_read_b128 v[148:151], v215 offset:17408
	ds_read_b128 v[152:155], v215 offset:18432
	ds_read_b128 v[156:159], v215 offset:19456
	ds_read_b128 v[178:181], v215 offset:20480
	ds_read_b128 v[182:185], v215 offset:21504
	ds_read_b128 v[186:189], v215 offset:22528
	ds_read_b128 v[190:193], v215 offset:23552
	s_add_i32 s12, s90, s67
	v_lshl_add_u64 v[210:211], s[14:15], 0, v[162:163]
	s_mov_b32 m0, s12
	s_nop 0
	global_load_lds_dwordx4 v[210:211], off
	v_lshl_add_u64 v[220:221], s[14:15], 0, v[166:167]
	s_add_i32 m0, s12, 0x2000
	s_nop 0
	global_load_lds_dwordx4 v[220:221], off
	s_mov_b32 m0, s68
	v_lshl_add_u64 v[222:223], s[16:17], 0, v[160:161]
	global_load_lds_dwordx4 v[222:223], off
	v_lshl_add_u64 v[224:225], s[16:17], 0, v[164:165]
	s_mov_b32 m0, s69
	s_nop 0
	global_load_lds_dwordx4 v[224:225], off
	s_add_u32 s12, s14, 0x40000
	s_addc_u32 s13, s15, 0
	s_add_i32 s50, s91, s67
	v_lshl_add_u64 v[254:255], s[12:13], 0, v[162:163]
	s_mov_b32 m0, s50
	s_nop 0
	global_load_lds_dwordx4 v[254:255], off
	v_lshl_add_u64 v[254:255], s[12:13], 0, v[166:167]
	s_add_i32 m0, s50, 0x2000
	s_nop 0
	global_load_lds_dwordx4 v[254:255], off
	s_waitcnt vmcnt(8)
	s_waitcnt lgkmcnt(0)
	s_barrier
; #define PG8_STAGE(bufoff, gbase, voff) do { _Pragma("unroll") for (int _i = 0; _i < 2; ++_i) \
;         __builtin_amdgcn_global_load_lds((const unsigned*)((const char*)(gbase) + (voff)[_i]), (LAS unsigned*)(lds + (bufoff) + ldsw + _i * 8192), 16, 0, 0); } while (0)
; #define PG8_LDA(dst, b, h) do { _Pragma("unroll") for (int m = 0; m < 4; ++m) _Pragma("unroll") for (int k = 0; k < 2; ++k) dst[m][k] = *(const LAS bf16x8*)(lds + PG8_SA(b, h) + aoff + m * 2048 + k * 1024); } while (0)
; #define PG8_LDB(dst, b, h) do { _Pragma("unroll") for (int n = 0; n < 2; ++n) _Pragma("unroll") for (int k = 0; k < 2; ++k) dst[n][k] = *(const LAS bf16x8*)(lds + PG8_SB(b, h) + boff + n * 2048 + k * 1024); } while (0)
; #define PG8_MMA(ai, bj, At, Bt) do { __builtin_amdgcn_s_setprio(1); _Pragma("unroll") for (int m = 0; m < 4; ++m) _Pragma("unroll") for (int n = 0; n < 2; ++n) _Pragma("unroll") for (int k = 0; k < 2; ++k) \
;         acc[ai][bj][m][n] = __builtin_amdgcn_mfma_f32_16x16x32_bf16(Bt[n][k], At[m][k], acc[ai][bj][m][n], 0, 0, 0); __builtin_amdgcn_s_setprio(0); } while (0)
; #define PG8_WAIT_V(n) asm volatile("s_waitcnt vmcnt(" #n ")" ::: "memory")
; #define PG8_WAIT_L(n) asm volatile("s_waitcnt lgkmcnt(" #n ")" ::: "memory")
; #define PG8_BAR __builtin_amdgcn_s_barrier()
; #define PG8_SCHED __builtin_amdgcn_sched_barrier(0)
; template <class Epi>
; __device__ __forceinline__ void gemm_phase(LAS unsigned char* lds, const Gemm g, const StaticOrder& S, const Epi& E, int wv) {
;     ...
;             PG8_LDA(At, 0, 1); PG8_STAGE(PG8_SA(0, 0), a2, voffA);
;             PG8_BAR; PG8_WAIT_L(0); PG8_MMA(1, 0, At, B0); PG8_BAR; PG8_SCHED;
;             PG8_STAGE(PG8_SB(0, 1), b2 + hstep, voffB);
;             PG8_WAIT_V(6); PG8_BAR; PG8_MMA(1, 1, At, B1); PG8_BAR;
;             PG8_LDB(B0, 1, 0); PG8_SCHED; PG8_LDA(At, 1, 0); PG8_STAGE(PG8_SA(0, 1), a2 + hstep, voffA);
;             PG8_WAIT_L(8); PG8_BAR; PG8_WAIT_L(0); PG8_MMA(0, 0, At, B0); PG8_BAR; PG8_SCHED;
;             PG8_LDB(B1, 1, 1); PG8_STAGE(PG8_SB(1, 0), b3, voffB);
;             PG8_BAR; PG8_WAIT_L(0); PG8_MMA(0, 1, At, B1); PG8_BAR;
;             PG8_LDA(At, 1, 1); PG8_STAGE(PG8_SA(1, 0), a3, voffA);
;             PG8_BAR; PG8_WAIT_L(0); PG8_MMA(1, 0, At, B0); PG8_BAR; PG8_SCHED;
	s_setprio 1
	v_mfma_f32_16x16x32_bf16 v[92:95], v[128:131], v[144:147], v[92:95]
	v_mfma_f32_16x16x32_bf16 v[28:31], v[136:139], v[144:147], v[28:31]
	v_mfma_f32_16x16x32_bf16 v[84:87], v[128:131], v[152:155], v[84:87]
	v_mfma_f32_16x16x32_bf16 v[20:23], v[136:139], v[152:155], v[20:23]
	v_mfma_f32_16x16x32_bf16 v[80:83], v[128:131], v[178:181], v[80:83]
	v_mfma_f32_16x16x32_bf16 v[16:19], v[136:139], v[178:181], v[16:19]
	v_mfma_f32_16x16x32_bf16 v[76:79], v[128:131], v[186:189], v[76:79]
	v_mfma_f32_16x16x32_bf16 v[12:15], v[136:139], v[186:189], v[12:15]
	v_mfma_f32_16x16x32_bf16 v[92:95], v[132:135], v[148:151], v[92:95]
	v_mfma_f32_16x16x32_bf16 v[28:31], v[140:143], v[148:151], v[28:31]
	v_mfma_f32_16x16x32_bf16 v[84:87], v[132:135], v[156:159], v[84:87]
	v_mfma_f32_16x16x32_bf16 v[20:23], v[140:143], v[156:159], v[20:23]
	v_mfma_f32_16x16x32_bf16 v[80:83], v[132:135], v[182:185], v[80:83]
	v_mfma_f32_16x16x32_bf16 v[16:19], v[140:143], v[182:185], v[16:19]
	v_mfma_f32_16x16x32_bf16 v[76:79], v[132:135], v[190:193], v[76:79]
	v_mfma_f32_16x16x32_bf16 v[12:15], v[140:143], v[190:193], v[12:15]
	v_mfma_f32_16x16x32_bf16 v[88:91], v[194:197], v[144:147], v[88:91]
	v_mfma_f32_16x16x32_bf16 v[24:27], v[202:205], v[144:147], v[24:27]
	v_mfma_f32_16x16x32_bf16 v[72:75], v[194:197], v[152:155], v[72:75]
	v_mfma_f32_16x16x32_bf16 v[8:11], v[202:205], v[152:155], v[8:11]
	v_mfma_f32_16x16x32_bf16 v[68:71], v[194:197], v[178:181], v[68:71]
	v_mfma_f32_16x16x32_bf16 v[4:7], v[202:205], v[178:181], v[4:7]
	v_mfma_f32_16x16x32_bf16 v[64:67], v[194:197], v[186:189], v[64:67]
	v_mfma_f32_16x16x32_bf16 v[0:3], v[202:205], v[186:189], v[0:3]
	v_mfma_f32_16x16x32_bf16 v[88:91], v[198:201], v[148:151], v[88:91]
	v_mfma_f32_16x16x32_bf16 v[24:27], v[206:209], v[148:151], v[24:27]
	v_mfma_f32_16x16x32_bf16 v[72:75], v[198:201], v[156:159], v[72:75]
	v_mfma_f32_16x16x32_bf16 v[8:11], v[206:209], v[156:159], v[8:11]
	v_mfma_f32_16x16x32_bf16 v[68:71], v[198:201], v[182:185], v[68:71]
	v_mfma_f32_16x16x32_bf16 v[4:7], v[206:209], v[182:185], v[4:7]
	v_mfma_f32_16x16x32_bf16 v[64:67], v[198:201], v[190:193], v[64:67]
	v_mfma_f32_16x16x32_bf16 v[0:3], v[206:209], v[190:193], v[0:3]
	s_setprio 0
	s_add_i32 s50, 0, 0x18000
	v_add_u32_e32 v140, s50, v213
	s_barrier
	ds_read_b128 v[128:131], v140
	ds_read_b128 v[132:135], v140 offset:1024
	ds_read_b128 v[136:139], v140 offset:2048
	ds_read_b128 v[140:143], v140 offset:3072
	s_add_u32 s12, s16, 0x40000
	s_addc_u32 s13, s17, 0
	ds_read_b128 v[144:147], v215 offset:32768
	ds_read_b128 v[148:151], v215 offset:33792
	ds_read_b128 v[152:155], v215 offset:34816
	ds_read_b128 v[156:159], v215 offset:35840
	ds_read_b128 v[178:181], v215 offset:36864
	ds_read_b128 v[182:185], v215 offset:37888
	ds_read_b128 v[186:189], v215 offset:38912
	ds_read_b128 v[190:193], v215 offset:39936
	s_mov_b32 m0, s70
	v_lshl_add_u64 v[252:253], s[12:13], 0, v[160:161]
	global_load_lds_dwordx4 v[252:253], off
	v_lshl_add_u64 v[252:253], s[12:13], 0, v[164:165]
	s_mov_b32 m0, s71
	s_nop 0
	global_load_lds_dwordx4 v[252:253], off
	s_add_i32 s16, 0, 0x1c000
	v_add_u32_e32 v168, s16, v213
	ds_read_b128 v[194:197], v168
	ds_read_b128 v[198:201], v168 offset:1024
	ds_read_b128 v[202:205], v168 offset:2048
	ds_read_b128 v[206:209], v168 offset:3072
	s_waitcnt vmcnt(8)
	s_waitcnt lgkmcnt(0)
	s_barrier
	s_setprio 1
	v_mfma_f32_16x16x32_bf16 v[124:127], v[128:131], v[144:147], v[124:127]
	v_mfma_f32_16x16x32_bf16 v[60:63], v[136:139], v[144:147], v[60:63]
	v_mfma_f32_16x16x32_bf16 v[116:119], v[128:131], v[152:155], v[116:119]
	v_mfma_f32_16x16x32_bf16 v[52:55], v[136:139], v[152:155], v[52:55]
	v_mfma_f32_16x16x32_bf16 v[112:115], v[128:131], v[178:181], v[112:115]
	v_mfma_f32_16x16x32_bf16 v[48:51], v[136:139], v[178:181], v[48:51]
	v_mfma_f32_16x16x32_bf16 v[108:111], v[128:131], v[186:189], v[108:111]
	v_mfma_f32_16x16x32_bf16 v[44:47], v[136:139], v[186:189], v[44:47]
	v_mfma_f32_16x16x32_bf16 v[124:127], v[132:135], v[148:151], v[124:127]
	v_mfma_f32_16x16x32_bf16 v[60:63], v[140:143], v[148:151], v[60:63]
	v_mfma_f32_16x16x32_bf16 v[116:119], v[132:135], v[156:159], v[116:119]
	v_mfma_f32_16x16x32_bf16 v[52:55], v[140:143], v[156:159], v[52:55]
	v_mfma_f32_16x16x32_bf16 v[112:115], v[132:135], v[182:185], v[112:115]
	v_mfma_f32_16x16x32_bf16 v[48:51], v[140:143], v[182:185], v[48:51]
	v_mfma_f32_16x16x32_bf16 v[108:111], v[132:135], v[190:193], v[108:111]
	v_mfma_f32_16x16x32_bf16 v[44:47], v[140:143], v[190:193], v[44:47]
	v_mfma_f32_16x16x32_bf16 v[120:123], v[194:197], v[144:147], v[120:123]
	v_mfma_f32_16x16x32_bf16 v[56:59], v[202:205], v[144:147], v[56:59]
	v_mfma_f32_16x16x32_bf16 v[104:107], v[194:197], v[152:155], v[104:107]
	v_mfma_f32_16x16x32_bf16 v[40:43], v[202:205], v[152:155], v[40:43]
	v_mfma_f32_16x16x32_bf16 v[100:103], v[194:197], v[178:181], v[100:103]
	v_mfma_f32_16x16x32_bf16 v[36:39], v[202:205], v[178:181], v[36:39]
	v_mfma_f32_16x16x32_bf16 v[96:99], v[194:197], v[186:189], v[96:99]
	v_mfma_f32_16x16x32_bf16 v[32:35], v[202:205], v[186:189], v[32:35]
	v_mfma_f32_16x16x32_bf16 v[120:123], v[198:201], v[148:151], v[120:123]
	v_mfma_f32_16x16x32_bf16 v[56:59], v[206:209], v[148:151], v[56:59]
	v_mfma_f32_16x16x32_bf16 v[104:107], v[198:201], v[156:159], v[104:107]
	v_mfma_f32_16x16x32_bf16 v[40:43], v[206:209], v[156:159], v[40:43]
	v_mfma_f32_16x16x32_bf16 v[100:103], v[198:201], v[182:185], v[100:103]
	v_mfma_f32_16x16x32_bf16 v[36:39], v[206:209], v[182:185], v[36:39]
	v_mfma_f32_16x16x32_bf16 v[96:99], v[198:201], v[190:193], v[96:99]
	v_mfma_f32_16x16x32_bf16 v[32:35], v[206:209], v[190:193], v[32:35]
	s_setprio 0
	s_barrier
; #define PG8_STAGE(bufoff, gbase, voff) do { _Pragma("unroll") for (int _i = 0; _i < 2; ++_i) \
;         __builtin_amdgcn_global_load_lds((const unsigned*)((const char*)(gbase) + (voff)[_i]), (LAS unsigned*)(lds + (bufoff) + ldsw + _i * 8192), 16, 0, 0); } while (0)
; #define PG8_LDA(dst, b, h) do { _Pragma("unroll") for (int m = 0; m < 4; ++m) _Pragma("unroll") for (int k = 0; k < 2; ++k) dst[m][k] = *(const LAS bf16x8*)(lds + PG8_SA(b, h) + aoff + m * 2048 + k * 1024); } while (0)
; #define PG8_LDB(dst, b, h) do { _Pragma("unroll") for (int n = 0; n < 2; ++n) _Pragma("unroll") for (int k = 0; k < 2; ++k) dst[n][k] = *(const LAS bf16x8*)(lds + PG8_SB(b, h) + boff + n * 2048 + k * 1024); } while (0)
; #define PG8_MMA(ai, bj, At, Bt) do { __builtin_amdgcn_s_setprio(1); _Pragma("unroll") for (int m = 0; m < 4; ++m) _Pragma("unroll") for (int n = 0; n < 2; ++n) _Pragma("unroll") for (int k = 0; k < 2; ++k) \
;         acc[ai][bj][m][n] = __builtin_amdgcn_mfma_f32_16x16x32_bf16(Bt[n][k], At[m][k], acc[ai][bj][m][n], 0, 0, 0); __builtin_amdgcn_s_setprio(0); } while (0)
; #define PG8_WAIT_V(n) asm volatile("s_waitcnt vmcnt(" #n ")" ::: "memory")
; #define PG8_WAIT_L(n) asm volatile("s_waitcnt lgkmcnt(" #n ")" ::: "memory")
; #define PG8_BAR __builtin_amdgcn_s_barrier()
; #define PG8_SCHED __builtin_amdgcn_sched_barrier(0)
; template <class Epi>
; __device__ __forceinline__ void gemm_phase(LAS unsigned char* lds, const Gemm g, const StaticOrder& S, const Epi& E, int wv) {
;     ...
;             PG8_LDB(B0, 1, 0); PG8_SCHED; PG8_LDA(At, 1, 0); PG8_STAGE(PG8_SA(0, 1), a2 + hstep, voffA);
;             PG8_WAIT_L(8); PG8_BAR; PG8_WAIT_L(0); PG8_MMA(0, 0, At, B0); PG8_BAR; PG8_SCHED;
;             PG8_LDB(B1, 1, 1); PG8_STAGE(PG8_SB(1, 0), b3, voffB);
;             PG8_BAR; PG8_WAIT_L(0); PG8_MMA(0, 1, At, B1); PG8_BAR;
;             PG8_LDA(At, 1, 1); PG8_STAGE(PG8_SA(1, 0), a3, voffA);
;             PG8_BAR; PG8_WAIT_L(0); PG8_MMA(1, 0, At, B0); PG8_BAR; PG8_SCHED;
;             PG8_STAGE(PG8_SB(1, 1), b3 + hstep, voffB);
;             PG8_WAIT_V(6); PG8_BAR; PG8_MMA(1, 1, At, B1); PG8_BAR;
	ds_read_b128 v[144:147], v215 offset:49152
	ds_read_b128 v[148:151], v215 offset:50176
	ds_read_b128 v[152:155], v215 offset:51200
	ds_read_b128 v[156:159], v215 offset:52224
	ds_read_b128 v[178:181], v215 offset:53248
	ds_read_b128 v[182:185], v215 offset:54272
	ds_read_b128 v[186:189], v215 offset:55296
	ds_read_b128 v[190:193], v215 offset:56320
	s_add_i32 s12, s50, s67
	v_lshl_add_u64 v[210:211], v[210:211], 0, s[30:31]
	s_mov_b32 m0, s12
	s_nop 0
	global_load_lds_dwordx4 v[210:211], off
	v_lshl_add_u64 v[210:211], v[220:221], 0, s[30:31]
	s_add_i32 m0, s12, 0x2000
	s_nop 0
	global_load_lds_dwordx4 v[210:211], off
	s_mov_b32 m0, s77
	v_lshl_add_u64 v[210:211], v[222:223], 0, s[30:31]
	global_load_lds_dwordx4 v[210:211], off
	v_lshl_add_u64 v[210:211], v[224:225], 0, s[30:31]
	s_mov_b32 m0, s78
	s_nop 0
	global_load_lds_dwordx4 v[210:211], off
	s_add_u32 s12, s14, 0x40080
	s_addc_u32 s13, s15, 0
	s_add_i32 s14, s16, s67
	v_lshl_add_u64 v[254:255], s[12:13], 0, v[162:163]
	s_mov_b32 m0, s14
	s_nop 0
	global_load_lds_dwordx4 v[254:255], off
	v_lshl_add_u64 v[254:255], s[12:13], 0, v[166:167]
	s_add_i32 m0, s14, 0x2000
	s_nop 0
	global_load_lds_dwordx4 v[254:255], off
	s_waitcnt vmcnt(8)
	s_waitcnt lgkmcnt(0)
	s_barrier
	s_setprio 1
	v_mfma_f32_16x16x32_bf16 v[92:95], v[128:131], v[144:147], v[92:95]
	v_mfma_f32_16x16x32_bf16 v[28:31], v[136:139], v[144:147], v[28:31]
	v_mfma_f32_16x16x32_bf16 v[84:87], v[128:131], v[152:155], v[84:87]
	v_mfma_f32_16x16x32_bf16 v[20:23], v[136:139], v[152:155], v[20:23]
	v_mfma_f32_16x16x32_bf16 v[80:83], v[128:131], v[178:181], v[80:83]
	v_mfma_f32_16x16x32_bf16 v[16:19], v[136:139], v[178:181], v[16:19]
	v_mfma_f32_16x16x32_bf16 v[76:79], v[128:131], v[186:189], v[76:79]
	v_mfma_f32_16x16x32_bf16 v[12:15], v[136:139], v[186:189], v[12:15]
	v_mfma_f32_16x16x32_bf16 v[92:95], v[132:135], v[148:151], v[92:95]
	v_mfma_f32_16x16x32_bf16 v[28:31], v[140:143], v[148:151], v[28:31]
	v_mfma_f32_16x16x32_bf16 v[84:87], v[132:135], v[156:159], v[84:87]
	v_mfma_f32_16x16x32_bf16 v[20:23], v[140:143], v[156:159], v[20:23]
	v_mfma_f32_16x16x32_bf16 v[80:83], v[132:135], v[182:185], v[80:83]
	v_mfma_f32_16x16x32_bf16 v[16:19], v[140:143], v[182:185], v[16:19]
	v_mfma_f32_16x16x32_bf16 v[76:79], v[132:135], v[190:193], v[76:79]
	v_mfma_f32_16x16x32_bf16 v[12:15], v[140:143], v[190:193], v[12:15]
	v_mfma_f32_16x16x32_bf16 v[88:91], v[194:197], v[144:147], v[88:91]
	v_mfma_f32_16x16x32_bf16 v[24:27], v[202:205], v[144:147], v[24:27]
	v_mfma_f32_16x16x32_bf16 v[72:75], v[194:197], v[152:155], v[72:75]
	v_mfma_f32_16x16x32_bf16 v[8:11], v[202:205], v[152:155], v[8:11]
	v_mfma_f32_16x16x32_bf16 v[68:71], v[194:197], v[178:181], v[68:71]
	v_mfma_f32_16x16x32_bf16 v[4:7], v[202:205], v[178:181], v[4:7]
	v_mfma_f32_16x16x32_bf16 v[64:67], v[194:197], v[186:189], v[64:67]
	v_mfma_f32_16x16x32_bf16 v[0:3], v[202:205], v[186:189], v[0:3]
	v_mfma_f32_16x16x32_bf16 v[88:91], v[198:201], v[148:151], v[88:91]
	v_mfma_f32_16x16x32_bf16 v[24:27], v[206:209], v[148:151], v[24:27]
	v_mfma_f32_16x16x32_bf16 v[72:75], v[198:201], v[156:159], v[72:75]
	v_mfma_f32_16x16x32_bf16 v[8:11], v[206:209], v[156:159], v[8:11]
	v_mfma_f32_16x16x32_bf16 v[68:71], v[198:201], v[182:185], v[68:71]
	v_mfma_f32_16x16x32_bf16 v[4:7], v[206:209], v[182:185], v[4:7]
	v_mfma_f32_16x16x32_bf16 v[64:67], v[198:201], v[190:193], v[64:67]
	v_mfma_f32_16x16x32_bf16 v[0:3], v[206:209], v[190:193], v[0:3]
	s_setprio 0
	s_add_i32 s49, s49, 2
	s_add_u32 s46, s46, 0x100
	s_addc_u32 s48, s48, 0
	s_cmp_gt_u32 s49, 13
	s_mov_b64 s[12:13], s[6:7]
	s_barrier
	s_cbranch_scc0 .LBB0_999
	v_cndmask_b32_e64 v128, 0, 1, s[34:35]
	s_mov_b32 s9, -1
	v_cmp_ne_u32_e64 s[6:7], 1, v128
	s_andn2_b64 vcc, exec, s[34:35]
	s_cbranch_vccnz .LBB0_1002
	s_barrier

; #define PG8_STAGE(bufoff, gbase, voff) do { _Pragma("unroll") for (int _i = 0; _i < 2; ++_i) \
;         __builtin_amdgcn_global_load_lds((const unsigned*)((const char*)(gbase) + (voff)[_i]), (LAS unsigned*)(lds + (bufoff) + ldsw + _i * 8192), 16, 0, 0); } while (0)
; #define PG8_WAIT_V(n) asm volatile("s_waitcnt vmcnt(" #n ")" ::: "memory")
; #define PG8_BAR __builtin_amdgcn_s_barrier()
; template <class Epi>
; __device__ __forceinline__ void gemm_phase(LAS unsigned char* lds, const Gemm g, const StaticOrder& S, const Epi& E, int wv) {
;     ...
;     for (int i = 0; i < 2; ++i) { int R, C; stage_rc(tid * 16 + i * 8192, R, C);
;         const int Ra = (R & ~63) + 4 * (R & 15) + ((R >> 4) & 3);
;         voffA[i] = (unsigned)(Ra * K + C) * 2u; voffB[i] = (unsigned)(R * K + C) * 2u; }
;     const size_t kstep = (size_t)(BK * 2);
;     const size_t hstep = (size_t)HALF * K * 2;
;     const size_t tstepA = (size_t)g.a_tile_rows * K * 2;
;     const size_t tstepB = 2 * hstep;
;     const unsigned ldsw = (unsigned)wid * 1024u;
;     const int aoff = lds_byte(wr * 64 + fr, fq * 8), boff = lds_byte(wc * 32 + fr, fq * 8);
;     ...
;     const char* cA = (const char*)g.A + (size_t)cur.pm * tstepA; const char* cB = (const char*)g.Bt + (size_t)cur.pn * tstepB;
;     PG8_STAGE(PG8_SB(0, 0), cB, voffB); PG8_STAGE(PG8_SA(0, 0), cA, voffA); PG8_STAGE(PG8_SB(0, 1), cB + hstep, voffB); PG8_STAGE(PG8_SA(0, 1), cA + hstep, voffA);
;     if (wr == 1) PG8_BAR;
;     PG8_WAIT_V(4); PG8_BAR;
;     PG8_STAGE(PG8_SB(1, 0), cB + kstep, voffB); PG8_STAGE(PG8_SA(1, 0), cA + kstep, voffA); PG8_STAGE(PG8_SB(1, 1), cB + hstep + kstep, voffB);
;     PG8_WAIT_V(6); PG8_BAR;
.LBB0_1110:
	s_add_u32 s14, s10, 0x10e37000
	s_addc_u32 s15, s11, 0
	s_lshl_b32 s5, s5, 5
	s_mov_b64 s[16:17], 0x80
	s_and_b32 s56, s5, 0x60
	s_add_i32 m0, s51, 0x18000
	v_lshl_add_u64 v[6:7], v[6:7], 0, s[16:17]
	s_lshl_b32 s55, s7, 6
	s_lshl_b32 s7, s7, 13
	s_lshl_b32 s5, s56, 7
	s_waitcnt vmcnt(2)
	s_barrier
	global_load_lds_dwordx4 v[6:7], off
	v_lshl_add_u64 v[4:5], v[4:5], 0, s[16:17]
	s_add_i32 m0, s51, 0x1a000
	s_add_i32 s57, s51, 0x8000
	s_add_i32 s58, s51, 0xa000
	global_load_lds_dwordx4 v[4:5], off
	v_lshl_add_u64 v[2:3], v[2:3], 0, s[16:17]
	s_mov_b32 m0, s57
	s_add_u32 s8, s40, 0xb0080
	global_load_lds_dwordx4 v[2:3], off
	v_lshl_add_u64 v[0:1], v[0:1], 0, s[16:17]
	s_mov_b32 m0, s58
	s_addc_u32 s9, s41, 0
	global_load_lds_dwordx4 v[0:1], off
	s_add_i32 m0, s51, 0x1c000
	v_lshl_add_u64 v[0:1], s[8:9], 0, v[146:147]
	global_load_lds_dwordx4 v[0:1], off
	v_lshl_add_u64 v[0:1], s[8:9], 0, v[150:151]
	s_add_i32 m0, s51, 0x1e000
	s_add_i32 s64, 0, 0x10000
	global_load_lds_dwordx4 v[0:1], off
	v_and_b32_e32 v0, 15, v8
	v_and_b32_e32 v1, 48, v8
	v_lshl_or_b32 v0, v0, 6, v1
	v_lshlrev_b32_e32 v1, 2, v8
	v_and_b32_e32 v1, 32, v1
	v_bitop3_b32 v2, v0, s7, v1 bitop3:0xde
	v_bitop3_b32 v164, s5, v0, v1 bitop3:0xf6
	v_add3_u32 v0, v11, v12, v13
	v_mul_lo_u32 v0, v0, s4
	v_or_b32_e32 v0, v0, v9
	v_add_lshl_u32 v154, v0, v10, 1
	v_add3_u32 v0, v16, v17, v18
	s_waitcnt vmcnt(6)
	v_mul_lo_u32 v0, v0, s4
	v_or_b32_e32 v0, v0, v14
	s_add_i32 s65, 0, 0x14000
	s_sext_i32_i8 s12, s6
	s_ashr_i32 s59, s55, 31
	s_ashr_i32 s60, s24, 31
	s_mov_b32 s61, s24
	v_mov_b32_e32 v155, v153
	v_add_lshl_u32 v156, v0, v15, 1
	v_mov_b32_e32 v157, v153
	v_mov_b64_e32 v[158:159], 0x200
	v_mov_b64_e32 v[160:161], 0x1ff
	v_add_u32_e32 v165, s64, v164
	v_add_u32_e32 v166, 0, v2
	v_add_u32_e32 v167, s65, v164
	s_mov_b32 s66, 0x164b000
	s_mov_b64 s[18:19], 0x1000
	s_movk_i32 s67, 0x1000
	s_mov_b64 s[20:21], 0x1800
	s_mov_b64 s[22:23], 0x40000
	s_mov_b32 s68, 0x40000
	s_mov_b64 s[28:29], 0x40800
	s_mov_b64 s[30:31], 0x41000
	s_mov_b32 s69, 0x41000
	s_mov_b64 s[34:35], 0x41800
	s_mov_b32 s70, 0
	s_barrier

; #define PG8_STAGE(bufoff, gbase, voff) do { _Pragma("unroll") for (int _i = 0; _i < 2; ++_i) \
;         __builtin_amdgcn_global_load_lds((const unsigned*)((const char*)(gbase) + (voff)[_i]), (LAS unsigned*)(lds + (bufoff) + ldsw + _i * 8192), 16, 0, 0); } while (0)
; #define PG8_LDA(dst, b, h) do { _Pragma("unroll") for (int m = 0; m < 4; ++m) _Pragma("unroll") for (int k = 0; k < 2; ++k) dst[m][k] = *(const LAS bf16x8*)(lds + PG8_SA(b, h) + aoff + m * 2048 + k * 1024); } while (0)
; #define PG8_LDB(dst, b, h) do { _Pragma("unroll") for (int n = 0; n < 2; ++n) _Pragma("unroll") for (int k = 0; k < 2; ++k) dst[n][k] = *(const LAS bf16x8*)(lds + PG8_SB(b, h) + boff + n * 2048 + k * 1024); } while (0)
; #define PG8_MMA(ai, bj, At, Bt) do { __builtin_amdgcn_s_setprio(1); _Pragma("unroll") for (int m = 0; m < 4; ++m) _Pragma("unroll") for (int n = 0; n < 2; ++n) _Pragma("unroll") for (int k = 0; k < 2; ++k) \
;         acc[ai][bj][m][n] = __builtin_amdgcn_mfma_f32_16x16x32_bf16(Bt[n][k], At[m][k], acc[ai][bj][m][n], 0, 0, 0); __builtin_amdgcn_s_setprio(0); } while (0)
; #define PG8_WAIT_V(n) asm volatile("s_waitcnt vmcnt(" #n ")" ::: "memory")
; #define PG8_WAIT_L(n) asm volatile("s_waitcnt lgkmcnt(" #n ")" ::: "memory")
; #define PG8_BAR __builtin_amdgcn_s_barrier()
; #define PG8_SCHED __builtin_amdgcn_sched_barrier(0)
; template <class Epi>
; __device__ __forceinline__ void gemm_phase(LAS unsigned char* lds, const Gemm g, const StaticOrder& S, const Epi& E, int wv) {
;     ...
;             PG8_LDB(B0, 0, 0); PG8_SCHED; PG8_LDA(At, 0, 0); PG8_STAGE(PG8_SA(1, 1), a1 + hstep, voffA);
;             PG8_WAIT_L(8); PG8_BAR; PG8_WAIT_L(0); PG8_MMA(0, 0, At, B0); PG8_BAR; PG8_SCHED;
;             PG8_LDB(B1, 0, 1); PG8_STAGE(PG8_SB(0, 0), b2, voffB);
;             PG8_BAR; PG8_WAIT_L(0); PG8_MMA(0, 1, At, B1); PG8_BAR;
;             PG8_LDA(At, 0, 1); PG8_STAGE(PG8_SA(0, 0), a2, voffA);
;             PG8_BAR; PG8_WAIT_L(0); PG8_MMA(1, 0, At, B0); PG8_BAR; PG8_SCHED;
;             PG8_STAGE(PG8_SB(0, 1), b2 + hstep, voffB);
;             PG8_WAIT_V(6); PG8_BAR; PG8_MMA(1, 1, At, B1); PG8_BAR;
.LBB0_1122:
	ds_read_b128 v[128:131], v165
	ds_read_b128 v[132:135], v165 offset:1024
	ds_read_b128 v[136:139], v165 offset:2048
	ds_read_b128 v[140:143], v165 offset:3072
	s_add_u32 s40, s38, 0xfff50080
	s_addc_u32 s41, s39, -1
	s_cmp_eq_u32 s74, 40
	s_cselect_b32 s43, s5, s41
	s_cselect_b32 s42, s4, s40
	s_cselect_b32 s41, s7, s73
	s_cselect_b32 s40, s6, s37
	ds_read_b128 v[168:171], v166
	ds_read_b128 v[172:175], v166 offset:1024
	ds_read_b128 v[176:179], v166 offset:2048
	ds_read_b128 v[180:183], v166 offset:3072
	ds_read_b128 v[184:187], v166 offset:4096
	ds_read_b128 v[188:191], v166 offset:5120
	ds_read_b128 v[192:195], v166 offset:6144
	ds_read_b128 v[196:199], v166 offset:7168
	ds_read_b128 v[200:203], v167
	ds_read_b128 v[204:207], v167 offset:1024
	ds_read_b128 v[208:211], v167 offset:2048
	ds_read_b128 v[212:215], v167 offset:3072
	v_lshl_add_u64 v[252:253], s[38:39], 0, v[154:155]
	s_add_i32 m0, s51, 0xc000
	s_nop 0
	global_load_lds_dwordx4 v[252:253], off
	v_lshl_add_u64 v[252:253], s[38:39], 0, v[156:157]
	s_add_i32 m0, s51, 0xe000
	s_nop 0
	global_load_lds_dwordx4 v[252:253], off
	s_waitcnt vmcnt(8)
	s_waitcnt lgkmcnt(0)
	s_barrier
	s_setprio 1
	v_mfma_f32_16x16x32_bf16 v[124:127], v[128:131], v[168:171], v[124:127]
	v_mfma_f32_16x16x32_bf16 v[120:123], v[136:139], v[168:171], v[120:123]
	v_mfma_f32_16x16x32_bf16 v[116:119], v[128:131], v[176:179], v[116:119]
	v_mfma_f32_16x16x32_bf16 v[112:115], v[136:139], v[176:179], v[112:115]
	v_mfma_f32_16x16x32_bf16 v[108:111], v[128:131], v[184:187], v[108:111]
	v_mfma_f32_16x16x32_bf16 v[96:99], v[136:139], v[184:187], v[96:99]
	v_mfma_f32_16x16x32_bf16 v[80:83], v[128:131], v[192:195], v[80:83]
	v_mfma_f32_16x16x32_bf16 v[72:75], v[136:139], v[192:195], v[72:75]
	v_mfma_f32_16x16x32_bf16 v[124:127], v[132:135], v[172:175], v[124:127]
	v_mfma_f32_16x16x32_bf16 v[120:123], v[140:143], v[172:175], v[120:123]
	v_mfma_f32_16x16x32_bf16 v[116:119], v[132:135], v[180:183], v[116:119]
	v_mfma_f32_16x16x32_bf16 v[112:115], v[140:143], v[180:183], v[112:115]
	v_mfma_f32_16x16x32_bf16 v[108:111], v[132:135], v[188:191], v[108:111]
	v_mfma_f32_16x16x32_bf16 v[96:99], v[140:143], v[188:191], v[96:99]
	v_mfma_f32_16x16x32_bf16 v[80:83], v[132:135], v[196:199], v[80:83]
	v_mfma_f32_16x16x32_bf16 v[72:75], v[140:143], v[196:199], v[72:75]
	v_mfma_f32_16x16x32_bf16 v[104:107], v[200:203], v[168:171], v[104:107]
	v_mfma_f32_16x16x32_bf16 v[100:103], v[208:211], v[168:171], v[100:103]
	v_mfma_f32_16x16x32_bf16 v[92:95], v[200:203], v[176:179], v[92:95]
	v_mfma_f32_16x16x32_bf16 v[88:91], v[208:211], v[176:179], v[88:91]
	v_mfma_f32_16x16x32_bf16 v[84:87], v[200:203], v[184:187], v[84:87]
	v_mfma_f32_16x16x32_bf16 v[76:79], v[208:211], v[184:187], v[76:79]
	v_mfma_f32_16x16x32_bf16 v[68:71], v[200:203], v[192:195], v[68:71]
	v_mfma_f32_16x16x32_bf16 v[64:67], v[208:211], v[192:195], v[64:67]
	v_mfma_f32_16x16x32_bf16 v[104:107], v[204:207], v[172:175], v[104:107]
	v_mfma_f32_16x16x32_bf16 v[100:103], v[212:215], v[172:175], v[100:103]
	v_mfma_f32_16x16x32_bf16 v[92:95], v[204:207], v[180:183], v[92:95]
	v_mfma_f32_16x16x32_bf16 v[88:91], v[212:215], v[180:183], v[88:91]
	v_mfma_f32_16x16x32_bf16 v[84:87], v[204:207], v[188:191], v[84:87]
	v_mfma_f32_16x16x32_bf16 v[76:79], v[212:215], v[188:191], v[76:79]
	v_mfma_f32_16x16x32_bf16 v[68:71], v[204:207], v[196:199], v[68:71]
	v_mfma_f32_16x16x32_bf16 v[64:67], v[212:215], v[196:199], v[64:67]
	s_setprio 0
	s_barrier
	ds_read_b128 v[168:171], v166 offset:16384
	ds_read_b128 v[172:175], v166 offset:17408
	ds_read_b128 v[176:179], v166 offset:18432
	ds_read_b128 v[180:183], v166 offset:19456
	ds_read_b128 v[184:187], v166 offset:20480
	ds_read_b128 v[188:191], v166 offset:21504
	ds_read_b128 v[192:195], v166 offset:22528
	ds_read_b128 v[196:199], v166 offset:23552
	s_add_i32 s75, s64, s50
	v_lshl_add_u64 v[162:163], s[40:41], 0, v[146:147]
	s_mov_b32 m0, s75
	s_nop 0
	global_load_lds_dwordx4 v[162:163], off
	v_lshl_add_u64 v[216:217], s[40:41], 0, v[150:151]
	s_add_i32 m0, s75, 0x2000
	s_nop 0
	global_load_lds_dwordx4 v[216:217], off
	s_mov_b32 m0, s51
	v_lshl_add_u64 v[218:219], s[42:43], 0, v[144:145]
	global_load_lds_dwordx4 v[218:219], off
	v_lshl_add_u64 v[220:221], s[42:43], 0, v[148:149]
	s_mov_b32 m0, s52
	s_nop 0
	global_load_lds_dwordx4 v[220:221], off
	s_add_u32 s76, s40, 0xb0000
	s_addc_u32 s77, s41, 0
	s_add_i32 s75, s65, s50
	v_lshl_add_u64 v[254:255], s[76:77], 0, v[146:147]
	s_mov_b32 m0, s75
	s_nop 0
	global_load_lds_dwordx4 v[254:255], off
	v_lshl_add_u64 v[254:255], s[76:77], 0, v[150:151]
	s_add_i32 m0, s75, 0x2000
	s_nop 0
	global_load_lds_dwordx4 v[254:255], off
	s_waitcnt vmcnt(8)
	s_waitcnt lgkmcnt(0)
	s_barrier
; #define PG8_STAGE(bufoff, gbase, voff) do { _Pragma("unroll") for (int _i = 0; _i < 2; ++_i) \
;         __builtin_amdgcn_global_load_lds((const unsigned*)((const char*)(gbase) + (voff)[_i]), (LAS unsigned*)(lds + (bufoff) + ldsw + _i * 8192), 16, 0, 0); } while (0)
; #define PG8_LDA(dst, b, h) do { _Pragma("unroll") for (int m = 0; m < 4; ++m) _Pragma("unroll") for (int k = 0; k < 2; ++k) dst[m][k] = *(const LAS bf16x8*)(lds + PG8_SA(b, h) + aoff + m * 2048 + k * 1024); } while (0)
; #define PG8_LDB(dst, b, h) do { _Pragma("unroll") for (int n = 0; n < 2; ++n) _Pragma("unroll") for (int k = 0; k < 2; ++k) dst[n][k] = *(const LAS bf16x8*)(lds + PG8_SB(b, h) + boff + n * 2048 + k * 1024); } while (0)
; #define PG8_MMA(ai, bj, At, Bt) do { __builtin_amdgcn_s_setprio(1); _Pragma("unroll") for (int m = 0; m < 4; ++m) _Pragma("unroll") for (int n = 0; n < 2; ++n) _Pragma("unroll") for (int k = 0; k < 2; ++k) \
;         acc[ai][bj][m][n] = __builtin_amdgcn_mfma_f32_16x16x32_bf16(Bt[n][k], At[m][k], acc[ai][bj][m][n], 0, 0, 0); __builtin_amdgcn_s_setprio(0); } while (0)
; #define PG8_WAIT_V(n) asm volatile("s_waitcnt vmcnt(" #n ")" ::: "memory")
; #define PG8_WAIT_L(n) asm volatile("s_waitcnt lgkmcnt(" #n ")" ::: "memory")
; #define PG8_BAR __builtin_amdgcn_s_barrier()
; #define PG8_SCHED __builtin_amdgcn_sched_barrier(0)
; template <class Epi>
; __device__ __forceinline__ void gemm_phase(LAS unsigned char* lds, const Gemm g, const StaticOrder& S, const Epi& E, int wv) {
;     ...
;             PG8_LDA(At, 0, 1); PG8_STAGE(PG8_SA(0, 0), a2, voffA);
;             PG8_BAR; PG8_WAIT_L(0); PG8_MMA(1, 0, At, B0); PG8_BAR; PG8_SCHED;
;             PG8_STAGE(PG8_SB(0, 1), b2 + hstep, voffB);
;             PG8_WAIT_V(6); PG8_BAR; PG8_MMA(1, 1, At, B1); PG8_BAR;
;             PG8_LDB(B0, 1, 0); PG8_SCHED; PG8_LDA(At, 1, 0); PG8_STAGE(PG8_SA(0, 1), a2 + hstep, voffA);
;             PG8_WAIT_L(8); PG8_BAR; PG8_WAIT_L(0); PG8_MMA(0, 0, At, B0); PG8_BAR; PG8_SCHED;
;             PG8_LDB(B1, 1, 1); PG8_STAGE(PG8_SB(1, 0), b3, voffB);
;             PG8_BAR; PG8_WAIT_L(0); PG8_MMA(0, 1, At, B1); PG8_BAR;
;             PG8_LDA(At, 1, 1); PG8_STAGE(PG8_SA(1, 0), a3, voffA);
;             PG8_BAR; PG8_WAIT_L(0); PG8_MMA(1, 0, At, B0); PG8_BAR; PG8_SCHED;
	s_setprio 1
	v_mfma_f32_16x16x32_bf16 v[60:63], v[128:131], v[168:171], v[60:63]
	v_mfma_f32_16x16x32_bf16 v[56:59], v[136:139], v[168:171], v[56:59]
	v_mfma_f32_16x16x32_bf16 v[48:51], v[128:131], v[176:179], v[48:51]
	v_mfma_f32_16x16x32_bf16 v[40:43], v[136:139], v[176:179], v[40:43]
	v_mfma_f32_16x16x32_bf16 v[32:35], v[128:131], v[184:187], v[32:35]
	v_mfma_f32_16x16x32_bf16 v[24:27], v[136:139], v[184:187], v[24:27]
	v_mfma_f32_16x16x32_bf16 v[16:19], v[128:131], v[192:195], v[16:19]
	v_mfma_f32_16x16x32_bf16 v[8:11], v[136:139], v[192:195], v[8:11]
	v_mfma_f32_16x16x32_bf16 v[60:63], v[132:135], v[172:175], v[60:63]
	v_mfma_f32_16x16x32_bf16 v[56:59], v[140:143], v[172:175], v[56:59]
	v_mfma_f32_16x16x32_bf16 v[48:51], v[132:135], v[180:183], v[48:51]
	v_mfma_f32_16x16x32_bf16 v[40:43], v[140:143], v[180:183], v[40:43]
	v_mfma_f32_16x16x32_bf16 v[32:35], v[132:135], v[188:191], v[32:35]
	v_mfma_f32_16x16x32_bf16 v[24:27], v[140:143], v[188:191], v[24:27]
	v_mfma_f32_16x16x32_bf16 v[16:19], v[132:135], v[196:199], v[16:19]
	v_mfma_f32_16x16x32_bf16 v[8:11], v[140:143], v[196:199], v[8:11]
	v_mfma_f32_16x16x32_bf16 v[52:55], v[200:203], v[168:171], v[52:55]
	v_mfma_f32_16x16x32_bf16 v[44:47], v[208:211], v[168:171], v[44:47]
	v_mfma_f32_16x16x32_bf16 v[36:39], v[200:203], v[176:179], v[36:39]
	v_mfma_f32_16x16x32_bf16 v[28:31], v[208:211], v[176:179], v[28:31]
	v_mfma_f32_16x16x32_bf16 v[20:23], v[200:203], v[184:187], v[20:23]
	v_mfma_f32_16x16x32_bf16 v[12:15], v[208:211], v[184:187], v[12:15]
	v_mfma_f32_16x16x32_bf16 v[4:7], v[200:203], v[192:195], v[4:7]
	v_mfma_f32_16x16x32_bf16 v[0:3], v[208:211], v[192:195], v[0:3]
	v_mfma_f32_16x16x32_bf16 v[52:55], v[204:207], v[172:175], v[52:55]
	v_mfma_f32_16x16x32_bf16 v[44:47], v[212:215], v[172:175], v[44:47]
	v_mfma_f32_16x16x32_bf16 v[36:39], v[204:207], v[180:183], v[36:39]
	v_mfma_f32_16x16x32_bf16 v[28:31], v[212:215], v[180:183], v[28:31]
	v_mfma_f32_16x16x32_bf16 v[20:23], v[204:207], v[188:191], v[20:23]
	v_mfma_f32_16x16x32_bf16 v[12:15], v[212:215], v[188:191], v[12:15]
	v_mfma_f32_16x16x32_bf16 v[4:7], v[204:207], v[196:199], v[4:7]
	v_mfma_f32_16x16x32_bf16 v[0:3], v[212:215], v[196:199], v[0:3]
	s_setprio 0
	s_add_i32 s75, 0, 0x18000
	v_add_u32_e32 v140, s75, v164
	s_barrier
	ds_read_b128 v[128:131], v140
	ds_read_b128 v[132:135], v140 offset:1024
	ds_read_b128 v[136:139], v140 offset:2048
	ds_read_b128 v[140:143], v140 offset:3072
	s_add_u32 s42, s42, 0xb0000
	s_addc_u32 s43, s43, 0
	ds_read_b128 v[168:171], v166 offset:32768
	ds_read_b128 v[172:175], v166 offset:33792
	ds_read_b128 v[176:179], v166 offset:34816
	ds_read_b128 v[180:183], v166 offset:35840
	ds_read_b128 v[184:187], v166 offset:36864
	ds_read_b128 v[188:191], v166 offset:37888
	ds_read_b128 v[192:195], v166 offset:38912
	ds_read_b128 v[196:199], v166 offset:39936
	s_mov_b32 m0, s53
	v_lshl_add_u64 v[252:253], s[42:43], 0, v[144:145]
	global_load_lds_dwordx4 v[252:253], off
	v_lshl_add_u64 v[252:253], s[42:43], 0, v[148:149]
	s_mov_b32 m0, s54
	s_nop 0
	global_load_lds_dwordx4 v[252:253], off
	s_add_i32 s42, 0, 0x1c000
	v_add_u32_e32 v152, s42, v164
	ds_read_b128 v[200:203], v152
	ds_read_b128 v[204:207], v152 offset:1024
	ds_read_b128 v[208:211], v152 offset:2048
	ds_read_b128 v[212:215], v152 offset:3072
	s_waitcnt vmcnt(8)
	s_waitcnt lgkmcnt(0)
	s_barrier
	s_setprio 1
	v_mfma_f32_16x16x32_bf16 v[124:127], v[128:131], v[168:171], v[124:127]
	v_mfma_f32_16x16x32_bf16 v[120:123], v[136:139], v[168:171], v[120:123]
	v_mfma_f32_16x16x32_bf16 v[116:119], v[128:131], v[176:179], v[116:119]
	v_mfma_f32_16x16x32_bf16 v[112:115], v[136:139], v[176:179], v[112:115]
	v_mfma_f32_16x16x32_bf16 v[108:111], v[128:131], v[184:187], v[108:111]
	v_mfma_f32_16x16x32_bf16 v[96:99], v[136:139], v[184:187], v[96:99]
	v_mfma_f32_16x16x32_bf16 v[80:83], v[128:131], v[192:195], v[80:83]
	v_mfma_f32_16x16x32_bf16 v[72:75], v[136:139], v[192:195], v[72:75]
	v_mfma_f32_16x16x32_bf16 v[124:127], v[132:135], v[172:175], v[124:127]
	v_mfma_f32_16x16x32_bf16 v[120:123], v[140:143], v[172:175], v[120:123]
	v_mfma_f32_16x16x32_bf16 v[116:119], v[132:135], v[180:183], v[116:119]
	v_mfma_f32_16x16x32_bf16 v[112:115], v[140:143], v[180:183], v[112:115]
	v_mfma_f32_16x16x32_bf16 v[108:111], v[132:135], v[188:191], v[108:111]
	v_mfma_f32_16x16x32_bf16 v[96:99], v[140:143], v[188:191], v[96:99]
	v_mfma_f32_16x16x32_bf16 v[80:83], v[132:135], v[196:199], v[80:83]
	v_mfma_f32_16x16x32_bf16 v[72:75], v[140:143], v[196:199], v[72:75]
	v_mfma_f32_16x16x32_bf16 v[104:107], v[200:203], v[168:171], v[104:107]
	v_mfma_f32_16x16x32_bf16 v[100:103], v[208:211], v[168:171], v[100:103]
	v_mfma_f32_16x16x32_bf16 v[92:95], v[200:203], v[176:179], v[92:95]
	v_mfma_f32_16x16x32_bf16 v[88:91], v[208:211], v[176:179], v[88:91]
	v_mfma_f32_16x16x32_bf16 v[84:87], v[200:203], v[184:187], v[84:87]
	v_mfma_f32_16x16x32_bf16 v[76:79], v[208:211], v[184:187], v[76:79]
	v_mfma_f32_16x16x32_bf16 v[68:71], v[200:203], v[192:195], v[68:71]
	v_mfma_f32_16x16x32_bf16 v[64:67], v[208:211], v[192:195], v[64:67]
	v_mfma_f32_16x16x32_bf16 v[104:107], v[204:207], v[172:175], v[104:107]
	v_mfma_f32_16x16x32_bf16 v[100:103], v[212:215], v[172:175], v[100:103]
	v_mfma_f32_16x16x32_bf16 v[92:95], v[204:207], v[180:183], v[92:95]
	v_mfma_f32_16x16x32_bf16 v[88:91], v[212:215], v[180:183], v[88:91]
	v_mfma_f32_16x16x32_bf16 v[84:87], v[204:207], v[188:191], v[84:87]
	v_mfma_f32_16x16x32_bf16 v[76:79], v[212:215], v[188:191], v[76:79]
	v_mfma_f32_16x16x32_bf16 v[68:71], v[204:207], v[196:199], v[68:71]
	v_mfma_f32_16x16x32_bf16 v[64:67], v[212:215], v[196:199], v[64:67]
	s_setprio 0
	s_barrier
; #define PG8_STAGE(bufoff, gbase, voff) do { _Pragma("unroll") for (int _i = 0; _i < 2; ++_i) \
;         __builtin_amdgcn_global_load_lds((const unsigned*)((const char*)(gbase) + (voff)[_i]), (LAS unsigned*)(lds + (bufoff) + ldsw + _i * 8192), 16, 0, 0); } while (0)
; #define PG8_LDA(dst, b, h) do { _Pragma("unroll") for (int m = 0; m < 4; ++m) _Pragma("unroll") for (int k = 0; k < 2; ++k) dst[m][k] = *(const LAS bf16x8*)(lds + PG8_SA(b, h) + aoff + m * 2048 + k * 1024); } while (0)
; #define PG8_LDB(dst, b, h) do { _Pragma("unroll") for (int n = 0; n < 2; ++n) _Pragma("unroll") for (int k = 0; k < 2; ++k) dst[n][k] = *(const LAS bf16x8*)(lds + PG8_SB(b, h) + boff + n * 2048 + k * 1024); } while (0)
; #define PG8_WAIT_V(n) asm volatile("s_waitcnt vmcnt(" #n ")" ::: "memory")
; #define PG8_WAIT_L(n) asm volatile("s_waitcnt lgkmcnt(" #n ")" ::: "memory")
; #define PG8_BAR __builtin_amdgcn_s_barrier()
; #define PG8_SCHED __builtin_amdgcn_sched_barrier(0)
; template <class Epi>
; __device__ __forceinline__ void gemm_phase(LAS unsigned char* lds, const Gemm g, const StaticOrder& S, const Epi& E, int wv) {
;     ...
;             PG8_LDB(B0, 1, 0); PG8_SCHED; PG8_LDA(At, 1, 0); PG8_STAGE(PG8_SA(0, 1), a2 + hstep, voffA);
;             PG8_WAIT_L(8); PG8_BAR; PG8_WAIT_L(0); PG8_MMA(0, 0, At, B0); PG8_BAR; PG8_SCHED;
;             PG8_LDB(B1, 1, 1); PG8_STAGE(PG8_SB(1, 0), b3, voffB);
;             PG8_BAR; PG8_WAIT_L(0); PG8_MMA(0, 1, At, B1); PG8_BAR;
;             PG8_LDA(At, 1, 1); PG8_STAGE(PG8_SA(1, 0), a3, voffA);
;             PG8_BAR; PG8_WAIT_L(0); PG8_MMA(1, 0, At, B0); PG8_BAR; PG8_SCHED;
;             PG8_STAGE(PG8_SB(1, 1), b3 + hstep, voffB);
;             PG8_WAIT_V(6); PG8_BAR; PG8_MMA(1, 1, At, B1); PG8_BAR;
;     __device__ __forceinline__ void operator()(const f32x4 (&acc)[2][2][4][2], const Unit& u, int wr, int wc, int fr, int fq) const {
;         const float* gate = (u.pm >= 64) ? gate1 : gate0;
;         f32x4 gv[2][2];
; #pragma unroll
;         for (int bj = 0; bj < 2; ++bj)
; #pragma unroll
;             for (int n = 0; n < 2; ++n) gv[bj][n] = *(const f32x4*)(gate + u.pn * 256 + bj * 128 + wc * 32 + n * 16 + 4 * fq);
; #pragma unroll
;         for (int ai = 0; ai < 2; ++ai)
; #pragma unroll
;             for (int m = 0; m < 4; ++m) {
;                 const size_t row = (size_t)u.pm * 256 + ai * 128 + wr * 64 + 4 * fr + m;
	ds_read_b128 v[168:171], v166 offset:49152
	ds_read_b128 v[172:175], v166 offset:50176
	ds_read_b128 v[176:179], v166 offset:51200
	ds_read_b128 v[180:183], v166 offset:52224
	ds_read_b128 v[184:187], v166 offset:53248
	ds_read_b128 v[188:191], v166 offset:54272
	ds_read_b128 v[192:195], v166 offset:55296
	ds_read_b128 v[196:199], v166 offset:56320
	s_add_i32 s43, s75, s50
	v_lshl_add_u64 v[162:163], v[162:163], 0, s[16:17]
	s_mov_b32 m0, s43
	s_nop 0
	global_load_lds_dwordx4 v[162:163], off
	v_lshl_add_u64 v[162:163], v[216:217], 0, s[16:17]
	s_add_i32 m0, s43, 0x2000
	s_nop 0
	global_load_lds_dwordx4 v[162:163], off
	s_mov_b32 m0, s57
	v_lshl_add_u64 v[162:163], v[218:219], 0, s[16:17]
	global_load_lds_dwordx4 v[162:163], off
	v_lshl_add_u64 v[162:163], v[220:221], 0, s[16:17]
	s_mov_b32 m0, s58
	s_nop 0
	global_load_lds_dwordx4 v[162:163], off
	s_add_u32 s40, s40, 0xb0080
	s_addc_u32 s41, s41, 0
	s_add_i32 s42, s42, s50
	v_lshl_add_u64 v[254:255], s[40:41], 0, v[146:147]
	s_mov_b32 m0, s42
	s_nop 0
	global_load_lds_dwordx4 v[254:255], off
	v_lshl_add_u64 v[254:255], s[40:41], 0, v[150:151]
	s_add_i32 m0, s42, 0x2000
	s_nop 0
	global_load_lds_dwordx4 v[254:255], off
	s_waitcnt vmcnt(8)
	s_waitcnt lgkmcnt(0)
	s_barrier
	s_setprio 1
	v_mfma_f32_16x16x32_bf16 v[60:63], v[128:131], v[168:171], v[60:63]
	v_mfma_f32_16x16x32_bf16 v[56:59], v[136:139], v[168:171], v[56:59]
	v_mfma_f32_16x16x32_bf16 v[48:51], v[128:131], v[176:179], v[48:51]
	v_mfma_f32_16x16x32_bf16 v[40:43], v[136:139], v[176:179], v[40:43]
	v_mfma_f32_16x16x32_bf16 v[32:35], v[128:131], v[184:187], v[32:35]
	v_mfma_f32_16x16x32_bf16 v[24:27], v[136:139], v[184:187], v[24:27]
	v_mfma_f32_16x16x32_bf16 v[16:19], v[128:131], v[192:195], v[16:19]
	v_mfma_f32_16x16x32_bf16 v[8:11], v[136:139], v[192:195], v[8:11]
	v_mfma_f32_16x16x32_bf16 v[60:63], v[132:135], v[172:175], v[60:63]
	v_mfma_f32_16x16x32_bf16 v[56:59], v[140:143], v[172:175], v[56:59]
	v_mfma_f32_16x16x32_bf16 v[48:51], v[132:135], v[180:183], v[48:51]
	v_mfma_f32_16x16x32_bf16 v[40:43], v[140:143], v[180:183], v[40:43]
	v_mfma_f32_16x16x32_bf16 v[32:35], v[132:135], v[188:191], v[32:35]
	v_mfma_f32_16x16x32_bf16 v[24:27], v[140:143], v[188:191], v[24:27]
	v_mfma_f32_16x16x32_bf16 v[16:19], v[132:135], v[196:199], v[16:19]
	v_mfma_f32_16x16x32_bf16 v[8:11], v[140:143], v[196:199], v[8:11]
	v_mfma_f32_16x16x32_bf16 v[52:55], v[200:203], v[168:171], v[52:55]
	v_mfma_f32_16x16x32_bf16 v[44:47], v[208:211], v[168:171], v[44:47]
	v_mfma_f32_16x16x32_bf16 v[36:39], v[200:203], v[176:179], v[36:39]
	v_mfma_f32_16x16x32_bf16 v[28:31], v[208:211], v[176:179], v[28:31]
	v_mfma_f32_16x16x32_bf16 v[20:23], v[200:203], v[184:187], v[20:23]
	v_mfma_f32_16x16x32_bf16 v[12:15], v[208:211], v[184:187], v[12:15]
	v_mfma_f32_16x16x32_bf16 v[4:7], v[200:203], v[192:195], v[4:7]
	v_mfma_f32_16x16x32_bf16 v[0:3], v[208:211], v[192:195], v[0:3]
	v_mfma_f32_16x16x32_bf16 v[52:55], v[204:207], v[172:175], v[52:55]
	v_mfma_f32_16x16x32_bf16 v[44:47], v[212:215], v[172:175], v[44:47]
	v_mfma_f32_16x16x32_bf16 v[36:39], v[204:207], v[180:183], v[36:39]
	v_mfma_f32_16x16x32_bf16 v[28:31], v[212:215], v[180:183], v[28:31]
	v_mfma_f32_16x16x32_bf16 v[20:23], v[204:207], v[188:191], v[20:23]
	v_mfma_f32_16x16x32_bf16 v[12:15], v[212:215], v[188:191], v[12:15]
	v_mfma_f32_16x16x32_bf16 v[4:7], v[204:207], v[196:199], v[4:7]
	v_mfma_f32_16x16x32_bf16 v[0:3], v[212:215], v[196:199], v[0:3]
	s_setprio 0
	s_add_i32 s74, s74, 2
	s_add_u32 s38, s38, 0x100
	s_addc_u32 s39, s39, 0
	s_add_u32 s37, s37, 0x100
	s_addc_u32 s73, s73, 0
	s_cmp_gt_u32 s74, 41
	s_barrier
	s_cbranch_scc0 .LBB0_1122
	s_mov_b32 s37, -1
	s_cmp_gt_i32 s36, 63
	v_mbcnt_lo_u32_b32 v128, s37, 0
	v_mbcnt_hi_u32_b32 v152, s37, v128
	s_cselect_b32 s37, s66, 0x1645000
	s_add_u32 s37, s10, s37
	s_addc_u32 s42, s11, 0
	s_lshl_b32 s38, s12, 8
	s_ashr_i32 s39, s38, 31
	s_lshl_b64 s[40:41], s[38:39], 2
	s_add_u32 s12, s37, s40
	s_addc_u32 s37, s42, s41
	s_lshl_b32 s40, s56, 2
	v_lshrrev_b32_e32 v128, 2, v152
	s_add_u32 s40, s12, s40
	v_and_b32_e32 v162, 28, v128
	s_addc_u32 s41, s37, 0
	v_lshlrev_b32_e32 v128, 2, v162
	global_load_dwordx4 v[140:143], v128, s[40:41]
	global_load_dwordx4 v[136:139], v128, s[40:41] offset:64
	global_load_dwordx4 v[132:135], v128, s[40:41] offset:512
	s_nop 0
	global_load_dwordx4 v[128:131], v128, s[40:41] offset:576
	s_ashr_i32 s37, s36, 31
	s_lshl_b64 s[36:37], s[36:37], 8
	s_add_u32 s12, s36, s55
	v_lshlrev_b32_e32 v163, 2, v152
	s_addc_u32 s36, s37, s59
	v_bfe_u32 v222, v152, 5, 1
	v_bfe_u32 v152, v152, 4, 1
	v_lshlrev_b32_e32 v222, 4, v222
	v_lshl_or_b32 v152, v152, 5, v222
	v_and_or_b32 v162, v163, 60, s12
	v_mov_b32_e32 v163, s36
	v_lshlrev_b64 v[162:163], 11, v[162:163]
	v_lshl_add_u64 v[162:163], s[14:15], 0, v[162:163]
	s_lshl_b32 s12, s56, 1
	v_lshl_add_u64 v[162:163], s[38:39], 1, v[162:163]
	v_lshl_add_u64 v[162:163], v[162:163], 0, s[12:13]
	v_lshl_add_u64 v[162:163], v[162:163], 0, v[152:153]
	v_lshl_add_u64 v[168:169], v[162:163], 0, s[18:19]
	v_lshl_add_u64 v[170:171], v[162:163], 0, s[22:23]
	s_mov_b32 s12, s71
	s_nop 0
	v_lshl_add_u64 v[222:223], v[162:163], 0, s[30:31]
	s_mov_b32 s36, s72
	s_mov_b64 s[40:41], s[6:7]
	s_mov_b64 s[38:39], s[4:5]
	s_waitcnt vmcnt(0)
; __device__ __forceinline__ unsigned pk2(float lo, float hi) { unsigned r; asm("v_cvt_pk_bf16_f32 %0, %1, %2" : "=v"(r) : "v"(lo), "v"(hi)); return r; }
;     __device__ __forceinline__ void operator()(const f32x4 (&acc)[2][2][4][2], const Unit& u, int wr, int wc, int fr, int fq) const {
;     ...
;                 for (int bj = 0; bj < 2; ++bj)
; #pragma unroll
;                     for (int n = 0; n < 2; ++n) {
;                         const f32x4 v = gv[bj][n] * acc[ai][bj][m][n];
;                         u32x2 w; w.x = pk2(v[0], v[1]); w.y = pk2(v[2], v[3]);
;                         *(u32x2*)(O + row * D + u.pn * 256 + bj * 128 + wc * 32 + n * 16 + 4 * fq) = w;
;                     }
;             }
	v_pk_mul_f32 v[124:125], v[124:125], v[140:141]
	v_pk_mul_f32 v[126:127], v[126:127], v[142:143]
	v_pk_mul_f32 v[120:121], v[120:121], v[136:137]
	v_pk_mul_f32 v[122:123], v[122:123], v[138:139]
	v_cvt_pk_bf16_f32 v124, v124, v125
	v_cvt_pk_bf16_f32 v125, v126, v127
	v_cvt_pk_bf16_f32 v126, v120, v121
	v_cvt_pk_bf16_f32 v127, v122, v123
	v_pk_mul_f32 v[104:105], v[104:105], v[132:133]
	v_pk_mul_f32 v[106:107], v[106:107], v[134:135]
	v_pk_mul_f32 v[100:101], v[100:101], v[128:129]
	v_pk_mul_f32 v[102:103], v[102:103], v[130:131]
	v_permlane16_swap_b32_e32 v124, v126
	v_permlane16_swap_b32_e32 v125, v127
	global_store_dwordx4 v[162:163], v[124:127], off
	v_cvt_pk_bf16_f32 v104, v104, v105
	v_cvt_pk_bf16_f32 v105, v106, v107
	v_cvt_pk_bf16_f32 v106, v100, v101
	v_cvt_pk_bf16_f32 v107, v102, v103
	v_pk_mul_f32 v[116:117], v[116:117], v[140:141]
	v_pk_mul_f32 v[118:119], v[118:119], v[142:143]
	v_pk_mul_f32 v[112:113], v[112:113], v[136:137]
	v_pk_mul_f32 v[114:115], v[114:115], v[138:139]
	v_permlane16_swap_b32_e32 v104, v106
	v_permlane16_swap_b32_e32 v105, v107
	global_store_dwordx4 v[162:163], v[104:107], off offset:256
	v_cvt_pk_bf16_f32 v116, v116, v117
	v_cvt_pk_bf16_f32 v117, v118, v119
	v_cvt_pk_bf16_f32 v118, v112, v113
	v_cvt_pk_bf16_f32 v119, v114, v115
	v_pk_mul_f32 v[92:93], v[92:93], v[132:133]
	v_pk_mul_f32 v[94:95], v[94:95], v[134:135]
	v_pk_mul_f32 v[88:89], v[88:89], v[128:129]
	v_pk_mul_f32 v[90:91], v[90:91], v[130:131]
	v_permlane16_swap_b32_e32 v116, v118
	v_permlane16_swap_b32_e32 v117, v119
	global_store_dwordx4 v[162:163], v[116:119], off offset:2048
	v_cvt_pk_bf16_f32 v92, v92, v93
	v_cvt_pk_bf16_f32 v93, v94, v95
	v_cvt_pk_bf16_f32 v94, v88, v89
	v_cvt_pk_bf16_f32 v95, v90, v91
	v_pk_mul_f32 v[108:109], v[108:109], v[140:141]
	v_pk_mul_f32 v[110:111], v[110:111], v[142:143]
	v_pk_mul_f32 v[96:97], v[96:97], v[136:137]
	v_pk_mul_f32 v[98:99], v[98:99], v[138:139]
	v_permlane16_swap_b32_e32 v92, v94
	v_permlane16_swap_b32_e32 v93, v95
	global_store_dwordx4 v[162:163], v[92:95], off offset:2304
	v_cvt_pk_bf16_f32 v108, v108, v109
	v_cvt_pk_bf16_f32 v109, v110, v111
	v_cvt_pk_bf16_f32 v110, v96, v97
	v_cvt_pk_bf16_f32 v111, v98, v99
	v_pk_mul_f32 v[84:85], v[84:85], v[132:133]
	v_pk_mul_f32 v[86:87], v[86:87], v[134:135]
	v_pk_mul_f32 v[76:77], v[76:77], v[128:129]
	v_pk_mul_f32 v[78:79], v[78:79], v[130:131]
	v_permlane16_swap_b32_e32 v108, v110
	v_permlane16_swap_b32_e32 v109, v111
	global_store_dwordx4 v[168:169], v[108:111], off
	v_cvt_pk_bf16_f32 v84, v84, v85
	v_cvt_pk_bf16_f32 v85, v86, v87
	v_cvt_pk_bf16_f32 v86, v76, v77
	v_cvt_pk_bf16_f32 v87, v78, v79
	v_pk_mul_f32 v[80:81], v[80:81], v[140:141]
	v_pk_mul_f32 v[82:83], v[82:83], v[142:143]
	v_pk_mul_f32 v[72:73], v[72:73], v[136:137]
	v_pk_mul_f32 v[74:75], v[74:75], v[138:139]
	v_permlane16_swap_b32_e32 v84, v86
	v_permlane16_swap_b32_e32 v85, v87
	global_store_dwordx4 v[168:169], v[84:87], off offset:256
	v_cvt_pk_bf16_f32 v80, v80, v81
	v_cvt_pk_bf16_f32 v81, v82, v83
	v_cvt_pk_bf16_f32 v82, v72, v73
	v_cvt_pk_bf16_f32 v83, v74, v75
	v_pk_mul_f32 v[68:69], v[68:69], v[132:133]
	v_pk_mul_f32 v[70:71], v[70:71], v[134:135]
	v_pk_mul_f32 v[64:65], v[64:65], v[128:129]
	v_pk_mul_f32 v[66:67], v[66:67], v[130:131]
	v_permlane16_swap_b32_e32 v80, v82
	v_permlane16_swap_b32_e32 v81, v83
	global_store_dwordx4 v[168:169], v[80:83], off offset:2048
	v_cvt_pk_bf16_f32 v68, v68, v69
	v_cvt_pk_bf16_f32 v69, v70, v71
	v_cvt_pk_bf16_f32 v70, v64, v65
	v_cvt_pk_bf16_f32 v71, v66, v67
	v_pk_mul_f32 v[60:61], v[60:61], v[140:141]
	v_pk_mul_f32 v[62:63], v[62:63], v[142:143]
	v_pk_mul_f32 v[56:57], v[56:57], v[136:137]
; __device__ __forceinline__ int lane_fresh() { unsigned m = ~0u; asm volatile("" : "+s"(m)); return (int)__builtin_amdgcn_mbcnt_hi(m, __builtin_amdgcn_mbcnt_lo(m, 0u)); }
; __device__ __forceinline__ unsigned pk2(float lo, float hi) { unsigned r; asm("v_cvt_pk_bf16_f32 %0, %1, %2" : "=v"(r) : "v"(lo), "v"(hi)); return r; }
; #define PG8_WAIT_V(n) asm volatile("s_waitcnt vmcnt(" #n ")" ::: "memory")
; #define PG8_BAR __builtin_amdgcn_s_barrier()
; template <class Epi>
; __device__ __forceinline__ void gemm_phase(LAS unsigned char* lds, const Gemm g, const StaticOrder& S, const Epi& E, int wv) {
;     ...
;         { const int ln2 = lane_fresh();
;           E(acc, cur, wr, wc, ln2 & 15, ln2 >> 4); }
;         if (!has_next) break;
; #pragma unroll
;         for (int a = 0; a < 2; ++a)
; #pragma unroll
;             for (int b = 0; b < 2; ++b)
; #pragma unroll
;                 for (int m = 0; m < 4; ++m)
; #pragma unroll
;                     for (int n = 0; n < 2; ++n) acc[a][b][m][n] = (f32x4){0.f, 0.f, 0.f, 0.f};
;         cur = nxt; cA = nA; cB = nB; ++ui;
;     }
;     PG8_WAIT_V(0);
;     if (wr == 0) PG8_BAR;
;     PG8_BAR;
;     __device__ __forceinline__ void operator()(const f32x4 (&acc)[2][2][4][2], const Unit& u, int wr, int wc, int fr, int fq) const {
;     ...
;                 for (int bj = 0; bj < 2; ++bj)
; #pragma unroll
;                     for (int n = 0; n < 2; ++n) {
;                         const f32x4 v = gv[bj][n] * acc[ai][bj][m][n];
;                         u32x2 w; w.x = pk2(v[0], v[1]); w.y = pk2(v[2], v[3]);
;                         *(u32x2*)(O + row * D + u.pn * 256 + bj * 128 + wc * 32 + n * 16 + 4 * fq) = w;
;                     }
;             }
	v_pk_mul_f32 v[58:59], v[58:59], v[138:139]
	v_permlane16_swap_b32_e32 v68, v70
	v_permlane16_swap_b32_e32 v69, v71
	global_store_dwordx4 v[168:169], v[68:71], off offset:2304
	v_cvt_pk_bf16_f32 v60, v60, v61
	v_cvt_pk_bf16_f32 v61, v62, v63
	v_cvt_pk_bf16_f32 v62, v56, v57
	v_cvt_pk_bf16_f32 v63, v58, v59
	v_pk_mul_f32 v[52:53], v[52:53], v[132:133]
	v_pk_mul_f32 v[54:55], v[54:55], v[134:135]
	v_pk_mul_f32 v[44:45], v[44:45], v[128:129]
	v_pk_mul_f32 v[46:47], v[46:47], v[130:131]
	v_permlane16_swap_b32_e32 v60, v62
	v_permlane16_swap_b32_e32 v61, v63
	global_store_dwordx4 v[170:171], v[60:63], off
	v_cvt_pk_bf16_f32 v52, v52, v53
	v_cvt_pk_bf16_f32 v53, v54, v55
	v_cvt_pk_bf16_f32 v54, v44, v45
	v_cvt_pk_bf16_f32 v55, v46, v47
	v_pk_mul_f32 v[48:49], v[48:49], v[140:141]
	v_pk_mul_f32 v[50:51], v[50:51], v[142:143]
	v_pk_mul_f32 v[40:41], v[40:41], v[136:137]
	v_pk_mul_f32 v[42:43], v[42:43], v[138:139]
	v_permlane16_swap_b32_e32 v52, v54
	v_permlane16_swap_b32_e32 v53, v55
	global_store_dwordx4 v[170:171], v[52:55], off offset:256
	v_cvt_pk_bf16_f32 v48, v48, v49
	v_cvt_pk_bf16_f32 v49, v50, v51
	v_cvt_pk_bf16_f32 v50, v40, v41
	v_cvt_pk_bf16_f32 v51, v42, v43
	v_pk_mul_f32 v[36:37], v[36:37], v[132:133]
	v_pk_mul_f32 v[38:39], v[38:39], v[134:135]
	v_pk_mul_f32 v[28:29], v[28:29], v[128:129]
	v_pk_mul_f32 v[30:31], v[30:31], v[130:131]
	v_permlane16_swap_b32_e32 v48, v50
	v_permlane16_swap_b32_e32 v49, v51
	global_store_dwordx4 v[170:171], v[48:51], off offset:2048
	v_cvt_pk_bf16_f32 v36, v36, v37
	v_cvt_pk_bf16_f32 v37, v38, v39
	v_cvt_pk_bf16_f32 v38, v28, v29
	v_cvt_pk_bf16_f32 v39, v30, v31
	v_pk_mul_f32 v[32:33], v[32:33], v[140:141]
	v_pk_mul_f32 v[34:35], v[34:35], v[142:143]
	v_pk_mul_f32 v[24:25], v[24:25], v[136:137]
	v_pk_mul_f32 v[26:27], v[26:27], v[138:139]
	v_permlane16_swap_b32_e32 v36, v38
	v_permlane16_swap_b32_e32 v37, v39
	global_store_dwordx4 v[170:171], v[36:39], off offset:2304
	v_cvt_pk_bf16_f32 v32, v32, v33
	v_cvt_pk_bf16_f32 v33, v34, v35
	v_cvt_pk_bf16_f32 v34, v24, v25
	v_cvt_pk_bf16_f32 v35, v26, v27
	v_pk_mul_f32 v[20:21], v[20:21], v[132:133]
	v_pk_mul_f32 v[22:23], v[22:23], v[134:135]
	v_pk_mul_f32 v[12:13], v[12:13], v[128:129]
	v_pk_mul_f32 v[14:15], v[14:15], v[130:131]
	v_permlane16_swap_b32_e32 v32, v34
	v_permlane16_swap_b32_e32 v33, v35
	global_store_dwordx4 v[222:223], v[32:35], off
	v_cvt_pk_bf16_f32 v20, v20, v21
	v_cvt_pk_bf16_f32 v21, v22, v23
	v_cvt_pk_bf16_f32 v22, v12, v13
	v_cvt_pk_bf16_f32 v23, v14, v15
	v_pk_mul_f32 v[16:17], v[16:17], v[140:141]
	v_pk_mul_f32 v[18:19], v[18:19], v[142:143]
	v_pk_mul_f32 v[8:9], v[8:9], v[136:137]
	v_pk_mul_f32 v[10:11], v[10:11], v[138:139]
	v_permlane16_swap_b32_e32 v20, v22
	v_permlane16_swap_b32_e32 v21, v23
	global_store_dwordx4 v[222:223], v[20:23], off offset:256
	v_cvt_pk_bf16_f32 v16, v16, v17
	v_cvt_pk_bf16_f32 v17, v18, v19
	v_cvt_pk_bf16_f32 v18, v8, v9
	v_cvt_pk_bf16_f32 v19, v10, v11
	v_pk_mul_f32 v[4:5], v[4:5], v[132:133]
	v_pk_mul_f32 v[6:7], v[6:7], v[134:135]
	v_pk_mul_f32 v[0:1], v[0:1], v[128:129]
	v_pk_mul_f32 v[2:3], v[2:3], v[130:131]
	v_permlane16_swap_b32_e32 v16, v18
	v_permlane16_swap_b32_e32 v17, v19
	global_store_dwordx4 v[222:223], v[16:19], off offset:2048
	v_cvt_pk_bf16_f32 v4, v4, v5
	v_cvt_pk_bf16_f32 v5, v6, v7
	v_cvt_pk_bf16_f32 v6, v0, v1
	v_cvt_pk_bf16_f32 v7, v2, v3
	s_nop 1
	v_permlane16_swap_b32_e32 v4, v6
	v_permlane16_swap_b32_e32 v5, v7
	global_store_dwordx4 v[222:223], v[4:7], off offset:2304
	s_and_b64 vcc, exec, s[8:9]
	s_cbranch_vccz .LBB0_1111
	s_waitcnt vmcnt(0)
	s_cmpk_gt_u32 s44, 0xff
	s_cbranch_scc1 .LBB0_1126
	s_barrier
